# kprio4 + S5 GLU as compact hand-written loops (8-deep B ring, 3-step A prefetch, row-contiguous stores via LDS)
# speedup vs baseline: 1.0046x; 1.0046x over previous
; #define S5_LDS_FENCE() do { __builtin_amdgcn_wave_barrier(); asm volatile("s_waitcnt lgkmcnt(0)" ::: "memory"); } while (0)
; template <bool WRITEH>
; __device__ __forceinline__ void s5_block(const S5Coef& C, const bf16x8 (&bm)[8], u32x4 uw, float* Hs, int lane, float& hr, float& hi) {
;     const bf16x8 ua = __builtin_bit_cast(bf16x8, uw);
; #pragma unroll
;     for (int nb = 0; nb < 8; ++nb) { const f32x4 d = __builtin_amdgcn_mfma_f32_16x16x32_bf16(ua, bm[nb], (f32x4){0.f, 0.f, 0.f, 0.f}, 0, 0, 0);
; #pragma unroll
;         for (int i = 0; i < 4; ++i) Hs[(4 * (lane >> 4) + i) * 132 + 16 * nb + (lane & 15)] = d[i]; }
;     S5_LDS_FENCE();
;     float bur[16], bui[16];
; #pragma unroll
;     for (int tl = 0; tl < 16; ++tl) { bur[tl] = Hs[tl * 132 + lane]; bui[tl] = Hs[tl * 132 + 64 + lane]; }
; #pragma unroll
;     for (int tl = 0; tl < 16; ++tl) { const float nr = C.ar * hr - C.ai * hi + bur[tl], ni = C.ar * hi + C.ai * hr + bui[tl]; hr = nr; hi = ni; bur[tl] = hr; bui[tl] = hi; }
; __device__ __forceinline__ void s5_unit(ArgsP A, int l, int unit, unsigned char* lds, int wave_, int lane_) {
;     ...
;     for (int gi = 0; gi < 4; ++gi) {
;         const int g = 4 * wave + gi;
;         S5Coef C; bf16x8 bm[8]; s5_fetch(A, l, g, lane, C, bm);
;         bf16x8 chl[8];
;         { const bf16x8* ct = (const bf16x8*)(A->ws + WS_S5T + (size_t)(l * 32 + g) * S5T_BYTES + 9216);
; #pragma unroll
;           for (int q = 0; q < 8; ++q) chl[q] = ct[q * 64 + lane]; }
;         const f32x2_t hin = ((const f32x2_t*)(A->ws + WS_S5H))[(size_t)((b * 64 + c) * 32 + g) * 64 + lane]; float hr = hin.x, hi = hin.y;
;         u32x4 uw[4];
; #pragma unroll
;         for (int blk = 0; blk < 4; ++blk) uw[blk] = s5_load_ua(PROJ, rowbase + 16 * blk, g, lane);
;         const float dv = A->in[20][l * 512 + 16 * g + (lane & 15)];
; #pragma unroll
;         for (int blk = 0; blk < 4; ++blk) {
;             unsigned short uraw[4];
; #pragma unroll
;             for (int i = 0; i < 4; ++i) uraw[i] = PROJ[(size_t)(rowbase + 16 * blk + 4 * (lane >> 4) + i) * INWP + C_S5 + 16 * g + (lane & 15)];
.LBB0_792:
	s_waitcnt lgkmcnt(0)
	v_lshl_add_u64 v[4:5], s[2:3], 0, v[98:99]
	v_add_co_u32_e32 v0, vcc, 0x2e7b0000, v4
	v_lshl_add_u64 v[66:67], s[2:3], 0, v[96:97]
	s_nop 0
	v_addc_co_u32_e32 v1, vcc, 0, v5, vcc
	global_load_dwordx4 v[32:35], v[0:1], off
	global_load_dwordx4 v[62:65], v[0:1], off offset:1024
	global_load_dwordx4 v[58:61], v[0:1], off offset:2048
	global_load_dwordx4 v[54:57], v[0:1], off offset:3072
	v_add_co_u32_e32 v0, vcc, 0x2e7b1000, v4
	v_ashrrev_i32_e32 v79, 31, v78
	s_nop 0
	v_addc_co_u32_e32 v1, vcc, 0, v5, vcc
	global_load_dwordx4 v[50:53], v[0:1], off
	global_load_dwordx4 v[46:49], v[0:1], off offset:1024
	global_load_dwordx4 v[42:45], v[0:1], off offset:2048
	global_load_dwordx4 v[38:41], v[0:1], off offset:3072
	v_add_co_u32_e32 v0, vcc, 0x2e7b2000, v4
	v_add_u32_e32 v115, 32, v112
	s_nop 0
	v_addc_co_u32_e32 v1, vcc, 0, v5, vcc
	global_load_dwordx4 v[34:37], v[0:1], off
	global_load_dwordx4 v[24:27], v[0:1], off offset:1024
	global_load_dwordx4 v[28:31], v[0:1], off offset:2048
	global_load_dwordx4 v[16:19], v[0:1], off offset:3072
	v_add_co_u32_e32 v0, vcc, 0x2e7b3000, v4
	v_add_u32_e32 v126, 0xd0, v112
	s_nop 0
	v_addc_co_u32_e32 v1, vcc, 0, v5, vcc
	v_add_co_u32_e32 v4, vcc, 0x2e7b4000, v4
	global_load_dwordx4 v[20:23], v[0:1], off
	global_load_dwordx4 v[8:11], v[0:1], off offset:1024
	global_load_dwordx4 v[12:15], v[0:1], off offset:2048
	s_nop 0
	global_load_dwordx4 v[0:3], v[0:1], off offset:3072
	v_addc_co_u32_e32 v5, vcc, 0, v5, vcc
	global_load_dwordx4 v[4:7], v[4:5], off
	s_load_dwordx2 s[6:7], s[26:27], 0xa0
	global_load_dwordx2 v[100:101], v[66:67], off
	v_lshl_add_u64 v[66:67], s[2:3], 0, v[94:95]
	global_load_dwordx4 v[116:119], v[66:67], off
	v_lshl_add_u64 v[66:67], s[2:3], 0, v[92:93]
	s_waitcnt lgkmcnt(0)
	v_lshl_add_u64 v[102:103], v[78:79], 2, s[6:7]
	global_load_dword v79, v[102:103], off
	v_lshl_add_u64 v[102:103], s[2:3], 0, v[86:87]
	v_add_co_u32_e32 v124, vcc, s12, v102
	global_load_dwordx4 v[74:77], v[66:67], off
	s_nop 0
	v_addc_co_u32_e32 v125, vcc, 0, v103, vcc
	global_load_ushort v162, v[124:125], off
	v_add_co_u32_e32 v124, vcc, s13, v102
	v_lshl_add_u64 v[66:67], s[2:3], 0, v[90:91]
	s_nop 0
	v_addc_co_u32_e32 v125, vcc, 0, v103, vcc
	global_load_ushort v131, v[124:125], off offset:512
	v_add_co_u32_e32 v124, vcc, s33, v102
	global_load_dwordx4 v[70:73], v[66:67], off
	s_nop 0
	v_addc_co_u32_e32 v125, vcc, 0, v103, vcc
	v_add_co_u32_e32 v102, vcc, s28, v102
	v_lshl_add_u64 v[66:67], s[2:3], 0, v[88:89]
	s_nop 0
	v_addc_co_u32_e32 v103, vcc, 0, v103, vcc
	global_load_dwordx4 v[66:69], v[66:67], off
	v_add_u32_e32 v127, 0xe0, v112
	global_load_ushort v130, v[124:125], off offset:1024
	global_load_ushort v129, v[102:103], off offset:1536
	v_add_u32_e32 v124, 0xb0, v112
	v_add_u32_e32 v125, 0xc0, v112
	v_add_u32_e32 v128, 0xf0, v112
	s_mov_b64 s[6:7], 0x4400
	v_add_u32_e32 v78, 16, v78
	v_lshl_add_u64 v[86:87], v[86:87], 0, 32
	v_lshl_add_u64 v[88:89], v[88:89], 0, 32
	v_lshl_add_u64 v[90:91], v[90:91], 0, 32
	v_lshl_add_u64 v[92:93], v[92:93], 0, 32
	v_lshl_add_u64 v[94:95], v[94:95], 0, 32
	v_lshl_add_u64 v[96:97], v[96:97], 0, s[14:15]
	v_lshl_add_u64 v[98:99], v[98:99], 0, s[6:7]
	s_waitcnt vmcnt(8)
	v_mfma_f32_16x16x32_bf16 v[120:123], v[116:119], v[62:65], 0
	s_nop 7
	ds_write_b32 v106, v120
	ds_write_b32 v106, v121 offset:528
	ds_write_b32 v106, v122 offset:1056
	ds_write_b32 v107, v123
	v_mfma_f32_16x16x32_bf16 v[120:123], v[116:119], v[58:61], 0
	s_nop 7
	ds_write_b32 v106, v120 offset:64
	ds_write_b32 v106, v121 offset:592
	ds_write_b32 v106, v122 offset:1120
	ds_write_b32 v107, v123 offset:64
	v_mfma_f32_16x16x32_bf16 v[120:123], v[116:119], v[54:57], 0
	s_nop 7
	ds_write_b32 v106, v120 offset:128
	ds_write_b32 v106, v121 offset:656
	ds_write_b32 v106, v122 offset:1184
	ds_write_b32 v107, v123 offset:128
	v_mfma_f32_16x16x32_bf16 v[120:123], v[116:119], v[50:53], 0
	s_nop 7
	ds_write2_b32 v108, v120, v121 offset1:132
	ds_write_b32 v108, v122 offset:1056
	ds_write_b32 v109, v123
	v_mfma_f32_16x16x32_bf16 v[120:123], v[116:119], v[46:49], 0
	s_nop 7
	ds_write_b32 v106, v120 offset:256
	ds_write_b32 v106, v121 offset:784
	ds_write_b32 v106, v122 offset:1312
	ds_write_b32 v107, v123 offset:256
	v_mfma_f32_16x16x32_bf16 v[120:123], v[116:119], v[42:45], 0
	s_nop 7
	ds_write_b32 v106, v120 offset:320
	ds_write_b32 v106, v121 offset:848
	ds_write_b32 v106, v122 offset:1376
	ds_write_b32 v107, v123 offset:320
	v_mfma_f32_16x16x32_bf16 v[120:123], v[116:119], v[38:41], 0
	s_nop 7
	ds_write_b32 v106, v120 offset:384
	ds_write_b32 v106, v121 offset:912
	ds_write_b32 v106, v122 offset:1440
	ds_write_b32 v107, v123 offset:384
	v_mfma_f32_16x16x32_bf16 v[116:119], v[116:119], v[34:37], 0
	s_nop 7
	ds_write2_b32 v110, v116, v117 offset1:132
	ds_write_b32 v110, v118 offset:1056
	ds_write_b32 v111, v119
	s_waitcnt lgkmcnt(0)
	ds_read2st64_b32 v[102:103], v112 offset1:1
	ds_read2_b32 v[132:133], v112 offset0:132 offset1:196
	v_mul_f32_e32 v163, v33, v101
	v_mul_f32_e32 v101, v32, v101
	v_fmac_f32_e32 v101, v33, v100
	v_fma_f32 v163, v32, v100, -v163
	s_waitcnt lgkmcnt(1)
	v_add_f32_e32 v100, v101, v103
	ds_read2st64_b32 v[134:135], v115 offset0:4 offset1:5
	v_add_f32_e32 v102, v163, v102
	v_mul_f32_e32 v103, v32, v100
	v_mul_f32_e32 v101, v33, v100
	v_fmac_f32_e32 v103, v33, v102
	v_fma_f32 v101, v32, v102, -v101
	s_waitcnt lgkmcnt(1)
	v_add_f32_e32 v103, v133, v103
	v_add_f32_e32 v101, v132, v101
	v_mul_f32_e32 v132, v33, v103
	v_add_u32_e32 v116, 48, v112
	v_fma_f32 v132, v32, v101, -v132
	ds_read2st64_b32 v[136:137], v116 offset0:6 offset1:7
	s_waitcnt lgkmcnt(1)
; __device__ __forceinline__ unsigned cvt_pk(float lo, float hi) { f32x2_t v = {lo, hi}; bf16x2_t b = __builtin_convertvector(v, bf16x2_t); return __builtin_bit_cast(unsigned, b); }
; __device__ __forceinline__ float bflo(unsigned w) { return __uint_as_float(w << 16); }
; __device__ __forceinline__ float bfhi(unsigned w) { return __uint_as_float(w & 0xffff0000u); }
; #define S5_LDS_FENCE() do { __builtin_amdgcn_wave_barrier(); asm volatile("s_waitcnt lgkmcnt(0)" ::: "memory"); } while (0)
; template <bool WRITEH>
; __device__ __forceinline__ void s5_block(const S5Coef& C, const bf16x8 (&bm)[8], u32x4 uw, float* Hs, int lane, float& hr, float& hi) {
;     ...
;     for (int tl = 0; tl < 16; ++tl) { bur[tl] = Hs[tl * 132 + lane]; bui[tl] = Hs[tl * 132 + 64 + lane]; }
; #pragma unroll
;     for (int tl = 0; tl < 16; ++tl) { const float nr = C.ar * hr - C.ai * hi + bur[tl], ni = C.ar * hi + C.ai * hr + bui[tl]; hr = nr; hi = ni; bur[tl] = hr; bui[tl] = hi; }
;     if (WRITEH) {
; #pragma unroll
;         for (int tl = 0; tl < 16; ++tl) { Hs[tl * 132 + lane] = bur[tl]; Hs[tl * 132 + 64 + lane] = bui[tl]; }
;     }
;     S5_LDS_FENCE();
; __device__ __forceinline__ void s5_unit(ArgsP A, int l, int unit, unsigned char* lds, int wave_, int lane_) {
;     ...
;             for (int ks = 0; ks < 4; ++ks) { const float* hp = Hs + (lane & 15) * 132 + 32 * ks + 8 * (lane >> 4); const f32x4 h0 = *(const f32x4*)hp, h1 = *(const f32x4*)(hp + 4);
;                 u32x4 wh; wh.x = cvt_pk(h0[0], h0[1]); wh.y = cvt_pk(h0[2], h0[3]); wh.z = cvt_pk(h1[0], h1[1]); wh.w = cvt_pk(h1[2], h1[3]);
;                 u32x4 wl; wl.x = cvt_pk(h0[0] - bflo(wh.x), h0[1] - bfhi(wh.x)); wl.y = cvt_pk(h0[2] - bflo(wh.y), h0[3] - bfhi(wh.y)); wl.z = cvt_pk(h1[0] - bflo(wh.z), h1[1] - bfhi(wh.z)); wl.w = cvt_pk(h1[2] - bflo(wh.w), h1[3] - bfhi(wh.w));
;                 const bf16x8 hh_ = __builtin_bit_cast(bf16x8, wh), hl_ = __builtin_bit_cast(bf16x8, wl);
	v_add_f32_e32 v134, v134, v132
	v_mul_f32_e32 v132, v32, v103
	v_fmac_f32_e32 v132, v33, v101
	v_add_f32_e32 v135, v135, v132
	v_mul_f32_e32 v132, v33, v135
	v_add_u32_e32 v117, 64, v112
	v_fma_f32 v132, v32, v134, -v132
	ds_read2st64_b32 v[138:139], v117 offset0:8 offset1:9
	s_waitcnt lgkmcnt(1)
	v_add_f32_e32 v136, v136, v132
	v_mul_f32_e32 v132, v32, v135
	v_fmac_f32_e32 v132, v33, v134
	v_add_f32_e32 v137, v137, v132
	v_mul_f32_e32 v132, v33, v137
	v_add_u32_e32 v118, 0x50, v112
	v_fma_f32 v132, v32, v136, -v132
	ds_read2st64_b32 v[140:141], v118 offset0:10 offset1:11
	s_waitcnt lgkmcnt(1)
	v_add_f32_e32 v138, v138, v132
	v_mul_f32_e32 v132, v32, v137
	v_fmac_f32_e32 v132, v33, v136
	v_add_f32_e32 v139, v139, v132
	v_mul_f32_e32 v132, v33, v139
	v_add_u32_e32 v119, 0x60, v112
	v_fma_f32 v132, v32, v138, -v132
	ds_read2st64_b32 v[142:143], v119 offset0:12 offset1:13
	s_waitcnt lgkmcnt(1)
	v_add_f32_e32 v140, v140, v132
	v_mul_f32_e32 v132, v32, v139
	v_fmac_f32_e32 v132, v33, v138
	v_add_f32_e32 v141, v141, v132
	v_mul_f32_e32 v132, v33, v141
	v_add_u32_e32 v120, 0x70, v112
	v_fma_f32 v132, v32, v140, -v132
	ds_read2st64_b32 v[144:145], v120 offset0:14 offset1:15
	s_waitcnt lgkmcnt(1)
	v_add_f32_e32 v142, v142, v132
	v_mul_f32_e32 v132, v32, v141
	v_fmac_f32_e32 v132, v33, v140
	v_add_f32_e32 v143, v143, v132
	v_mul_f32_e32 v132, v33, v143
	v_add_u32_e32 v121, 0x80, v112
	v_fma_f32 v132, v32, v142, -v132
	ds_read2st64_b32 v[146:147], v121 offset0:16 offset1:17
	s_waitcnt lgkmcnt(1)
	v_add_f32_e32 v144, v144, v132
	v_mul_f32_e32 v132, v32, v143
	v_fmac_f32_e32 v132, v33, v142
	v_add_f32_e32 v145, v145, v132
	v_mul_f32_e32 v132, v33, v145
	v_add_u32_e32 v122, 0x90, v112
	v_fma_f32 v132, v32, v144, -v132
	ds_read2st64_b32 v[148:149], v122 offset0:18 offset1:19
	s_waitcnt lgkmcnt(1)
	v_add_f32_e32 v146, v146, v132
	v_mul_f32_e32 v132, v32, v145
	v_fmac_f32_e32 v132, v33, v144
	v_add_f32_e32 v147, v147, v132
	v_mul_f32_e32 v132, v33, v147
	v_add_u32_e32 v123, 0xa0, v112
	v_fma_f32 v132, v32, v146, -v132
	ds_read2st64_b32 v[150:151], v123 offset0:20 offset1:21
	s_waitcnt lgkmcnt(1)
	v_add_f32_e32 v148, v148, v132
	v_mul_f32_e32 v132, v32, v147
	v_fmac_f32_e32 v132, v33, v146
	v_add_f32_e32 v149, v149, v132
	v_mul_f32_e32 v132, v33, v149
	v_fma_f32 v132, v32, v148, -v132
	ds_read2st64_b32 v[152:153], v124 offset0:22 offset1:23
	s_waitcnt lgkmcnt(1)
	v_add_f32_e32 v150, v150, v132
	v_mul_f32_e32 v132, v32, v149
	v_fmac_f32_e32 v132, v33, v148
	v_add_f32_e32 v151, v151, v132
	v_mul_f32_e32 v132, v33, v151
	v_fma_f32 v132, v32, v150, -v132
	ds_read2st64_b32 v[154:155], v125 offset0:24 offset1:25
	s_waitcnt lgkmcnt(1)
	v_add_f32_e32 v152, v152, v132
	v_mul_f32_e32 v132, v32, v151
	v_fmac_f32_e32 v132, v33, v150
	v_add_f32_e32 v153, v153, v132
	v_mul_f32_e32 v132, v33, v153
	v_fma_f32 v132, v32, v152, -v132
	ds_read2st64_b32 v[156:157], v126 offset0:26 offset1:27
	s_waitcnt lgkmcnt(1)
	v_add_f32_e32 v154, v154, v132
	v_mul_f32_e32 v132, v32, v153
	v_fmac_f32_e32 v132, v33, v152
	v_add_f32_e32 v155, v155, v132
	v_mul_f32_e32 v132, v33, v155
	v_fma_f32 v132, v32, v154, -v132
	ds_read2st64_b32 v[158:159], v127 offset0:28 offset1:29
	s_waitcnt lgkmcnt(1)
	v_add_f32_e32 v156, v156, v132
	v_mul_f32_e32 v132, v32, v155
	v_fmac_f32_e32 v132, v33, v154
	v_add_f32_e32 v157, v157, v132
	v_mul_f32_e32 v132, v33, v157
	v_fma_f32 v132, v32, v156, -v132
	ds_read2st64_b32 v[160:161], v128 offset0:30 offset1:31
	s_waitcnt lgkmcnt(1)
	v_add_f32_e32 v158, v158, v132
	v_mul_f32_e32 v132, v32, v157
	v_fmac_f32_e32 v132, v33, v156
	v_add_f32_e32 v159, v159, v132
	v_mul_f32_e32 v132, v33, v159
	v_mul_f32_e32 v133, v32, v159
	v_fma_f32 v132, v32, v158, -v132
	v_fmac_f32_e32 v133, v33, v158
	s_waitcnt lgkmcnt(0)
	v_add_f32_e32 v132, v160, v132
	v_add_f32_e32 v133, v161, v133
	ds_write2st64_b32 v112, v102, v100 offset1:1
	ds_write2_b32 v112, v101, v103 offset0:132 offset1:196
	ds_write2st64_b32 v115, v134, v135 offset0:4 offset1:5
	ds_write2st64_b32 v116, v136, v137 offset0:6 offset1:7
	ds_write2st64_b32 v117, v138, v139 offset0:8 offset1:9
	ds_write2st64_b32 v118, v140, v141 offset0:10 offset1:11
	ds_write2st64_b32 v119, v142, v143 offset0:12 offset1:13
	ds_write2st64_b32 v120, v144, v145 offset0:14 offset1:15
	ds_write2st64_b32 v121, v146, v147 offset0:16 offset1:17
	ds_write2st64_b32 v122, v148, v149 offset0:18 offset1:19
	ds_write2st64_b32 v123, v150, v151 offset0:20 offset1:21
	ds_write2st64_b32 v124, v152, v153 offset0:22 offset1:23
	ds_write2st64_b32 v125, v154, v155 offset0:24 offset1:25
	ds_write2st64_b32 v126, v156, v157 offset0:26 offset1:27
	ds_write2st64_b32 v127, v158, v159 offset0:28 offset1:29
	ds_write2st64_b32 v128, v132, v133 offset0:30 offset1:31
	s_waitcnt lgkmcnt(0)
	ds_read_b128 v[100:103], v113
	ds_read_b128 v[134:137], v113 offset:16
	s_waitcnt vmcnt(4)
	v_lshlrev_b32_e32 v131, 16, v131
	v_mul_f32_e32 v160, v33, v133
	v_fma_f32 v160, v32, v132, -v160
	s_waitcnt lgkmcnt(1)
	v_cvt_pk_bf16_f32 v138, v100, v101
	v_cvt_pk_bf16_f32 v139, v102, v103
	v_lshlrev_b32_e32 v142, 16, v138
	v_and_b32_e32 v143, 0xffff0000, v138
	v_pk_add_f32 v[100:101], v[100:101], v[142:143] neg_lo:[0,1] neg_hi:[0,1]
	v_lshlrev_b32_e32 v142, 16, v139
	v_and_b32_e32 v143, 0xffff0000, v139
	s_waitcnt lgkmcnt(0)
; __device__ __forceinline__ unsigned cvt_pk(float lo, float hi) { f32x2_t v = {lo, hi}; bf16x2_t b = __builtin_convertvector(v, bf16x2_t); return __builtin_bit_cast(unsigned, b); }
; __device__ __forceinline__ float bf2f(unsigned short h) { return __uint_as_float(((unsigned)h) << 16); }
; __device__ __forceinline__ float bflo(unsigned w) { return __uint_as_float(w << 16); }
; __device__ __forceinline__ float bfhi(unsigned w) { return __uint_as_float(w & 0xffff0000u); }
; __device__ __forceinline__ unsigned short f2bf(float f) { return (unsigned short)(cvt_pk(f, 0.f) & 0xffffu); }
; __device__ __forceinline__ float fast_exp2(float x) { return __builtin_amdgcn_exp2f(x); }
; __device__ __forceinline__ float gelu_tanh(float x) {
;     const float z = 0.7978845608028654f * (x + 0.044715f * x * x * x);
;     const float e = fast_exp2(2.f * z * LOG2E);
;     const float th = 1.f - 2.f * fast_rcp(1.f + e);
;     return 0.5f * x * (1.f + th);
; }
; __device__ __forceinline__ void s5_unit(ArgsP A, int l, int unit, unsigned char* lds, int wave_, int lane_) {
;     ...
;             for (int ks = 0; ks < 4; ++ks) { const float* hp = Hs + (lane & 15) * 132 + 32 * ks + 8 * (lane >> 4); const f32x4 h0 = *(const f32x4*)hp, h1 = *(const f32x4*)(hp + 4);
;                 u32x4 wh; wh.x = cvt_pk(h0[0], h0[1]); wh.y = cvt_pk(h0[2], h0[3]); wh.z = cvt_pk(h1[0], h1[1]); wh.w = cvt_pk(h1[2], h1[3]);
;                 u32x4 wl; wl.x = cvt_pk(h0[0] - bflo(wh.x), h0[1] - bfhi(wh.x)); wl.y = cvt_pk(h0[2] - bflo(wh.y), h0[3] - bfhi(wh.y)); wl.z = cvt_pk(h1[0] - bflo(wh.z), h1[1] - bfhi(wh.z)); wl.w = cvt_pk(h1[2] - bflo(wh.w), h1[3] - bfhi(wh.w));
;                 const bf16x8 hh_ = __builtin_bit_cast(bf16x8, wh), hl_ = __builtin_bit_cast(bf16x8, wl);
;                 y = __builtin_amdgcn_mfma_f32_16x16x32_bf16(hh_, chl[2 * ks], y, 0, 0, 0); y2 = __builtin_amdgcn_mfma_f32_16x16x32_bf16(hh_, chl[2 * ks + 1], y2, 0, 0, 0);
;                 y2 = __builtin_amdgcn_mfma_f32_16x16x32_bf16(hl_, chl[2 * ks], y2, 0, 0, 0); }
;             y = y + y2;
; #pragma unroll
;             for (int i = 0; i < 4; ++i) { const int t = 16 * blk + 4 * (lane >> 4) + i; const int col = 16 * g + (lane & 15);
;                 const float uval = bf2f(uraw[i]); const float v = gelu_tanh(y[i] + dv * uval); ys[t * YS_STRIDE + col] = f2bf(v); }
	v_cvt_pk_bf16_f32 v140, v134, v135
	v_cvt_pk_bf16_f32 v141, v136, v137
	v_pk_add_f32 v[102:103], v[102:103], v[142:143] neg_lo:[0,1] neg_hi:[0,1]
	v_cvt_pk_bf16_f32 v100, v100, v101
	v_cvt_pk_bf16_f32 v101, v102, v103
	v_lshlrev_b32_e32 v102, 16, v140
	v_and_b32_e32 v103, 0xffff0000, v140
	v_pk_add_f32 v[102:103], v[134:135], v[102:103] neg_lo:[0,1] neg_hi:[0,1]
	v_lshlrev_b32_e32 v134, 16, v141
	v_and_b32_e32 v135, 0xffff0000, v141
	v_pk_add_f32 v[134:135], v[136:137], v[134:135] neg_lo:[0,1] neg_hi:[0,1]
	v_cvt_pk_bf16_f32 v102, v102, v103
	v_cvt_pk_bf16_f32 v103, v134, v135
	v_mfma_f32_16x16x32_bf16 v[134:137], v[138:141], v[24:27], 0
	v_mfma_f32_16x16x32_bf16 v[138:141], v[138:141], v[28:31], 0
	v_mfma_f32_16x16x32_bf16 v[100:103], v[100:103], v[24:27], v[138:141]
	s_nop 6
	ds_read_b128 v[138:141], v113 offset:128
	ds_read_b128 v[142:145], v113 offset:144
	s_waitcnt lgkmcnt(1)
	v_cvt_pk_bf16_f32 v146, v138, v139
	v_cvt_pk_bf16_f32 v147, v140, v141
	v_lshlrev_b32_e32 v150, 16, v146
	v_and_b32_e32 v151, 0xffff0000, v146
	v_pk_add_f32 v[138:139], v[138:139], v[150:151] neg_lo:[0,1] neg_hi:[0,1]
	v_lshlrev_b32_e32 v150, 16, v147
	v_and_b32_e32 v151, 0xffff0000, v147
	s_waitcnt lgkmcnt(0)
	v_cvt_pk_bf16_f32 v148, v142, v143
	v_cvt_pk_bf16_f32 v149, v144, v145
	v_pk_add_f32 v[140:141], v[140:141], v[150:151] neg_lo:[0,1] neg_hi:[0,1]
	v_cvt_pk_bf16_f32 v138, v138, v139
	v_cvt_pk_bf16_f32 v139, v140, v141
	v_lshlrev_b32_e32 v140, 16, v148
	v_and_b32_e32 v141, 0xffff0000, v148
	v_pk_add_f32 v[140:141], v[142:143], v[140:141] neg_lo:[0,1] neg_hi:[0,1]
	v_lshlrev_b32_e32 v142, 16, v149
	v_and_b32_e32 v143, 0xffff0000, v149
	v_pk_add_f32 v[142:143], v[144:145], v[142:143] neg_lo:[0,1] neg_hi:[0,1]
	v_cvt_pk_bf16_f32 v140, v140, v141
	v_cvt_pk_bf16_f32 v141, v142, v143
	v_mfma_f32_16x16x32_bf16 v[100:103], v[146:149], v[20:23], v[100:103]
	s_nop 0
	v_mfma_f32_16x16x32_bf16 v[100:103], v[138:141], v[16:19], v[100:103]
	ds_read_b128 v[138:141], v113 offset:256
	ds_read_b128 v[142:145], v113 offset:272
	v_mfma_f32_16x16x32_bf16 v[134:137], v[146:149], v[16:19], v[134:137]
	s_waitcnt lgkmcnt(1)
	v_cvt_pk_bf16_f32 v146, v138, v139
	v_cvt_pk_bf16_f32 v147, v140, v141
	v_lshlrev_b32_e32 v150, 16, v146
	v_and_b32_e32 v151, 0xffff0000, v146
	v_pk_add_f32 v[138:139], v[138:139], v[150:151] neg_lo:[0,1] neg_hi:[0,1]
	v_lshlrev_b32_e32 v150, 16, v147
	v_and_b32_e32 v151, 0xffff0000, v147
	s_waitcnt lgkmcnt(0)
	v_cvt_pk_bf16_f32 v148, v142, v143
	v_cvt_pk_bf16_f32 v149, v144, v145
	v_pk_add_f32 v[140:141], v[140:141], v[150:151] neg_lo:[0,1] neg_hi:[0,1]
	v_cvt_pk_bf16_f32 v138, v138, v139
	v_cvt_pk_bf16_f32 v139, v140, v141
	v_lshlrev_b32_e32 v140, 16, v148
	v_and_b32_e32 v141, 0xffff0000, v148
	v_pk_add_f32 v[140:141], v[142:143], v[140:141] neg_lo:[0,1] neg_hi:[0,1]
	v_lshlrev_b32_e32 v142, 16, v149
	v_and_b32_e32 v143, 0xffff0000, v149
	v_pk_add_f32 v[142:143], v[144:145], v[142:143] neg_lo:[0,1] neg_hi:[0,1]
	v_cvt_pk_bf16_f32 v140, v140, v141
	v_cvt_pk_bf16_f32 v141, v142, v143
	v_mfma_f32_16x16x32_bf16 v[100:103], v[146:149], v[12:15], v[100:103]
	s_nop 0
	v_mfma_f32_16x16x32_bf16 v[100:103], v[138:141], v[8:11], v[100:103]
	ds_read_b128 v[138:141], v113 offset:384
	ds_read_b128 v[142:145], v113 offset:400
	v_mfma_f32_16x16x32_bf16 v[134:137], v[146:149], v[8:11], v[134:137]
	s_waitcnt lgkmcnt(1)
	v_cvt_pk_bf16_f32 v146, v138, v139
	v_cvt_pk_bf16_f32 v147, v140, v141
	v_lshlrev_b32_e32 v150, 16, v146
	v_and_b32_e32 v151, 0xffff0000, v146
	v_pk_add_f32 v[138:139], v[138:139], v[150:151] neg_lo:[0,1] neg_hi:[0,1]
	v_lshlrev_b32_e32 v150, 16, v147
	v_and_b32_e32 v151, 0xffff0000, v147
	s_waitcnt lgkmcnt(0)
	v_cvt_pk_bf16_f32 v148, v142, v143
	v_cvt_pk_bf16_f32 v149, v144, v145
	v_pk_add_f32 v[140:141], v[140:141], v[150:151] neg_lo:[0,1] neg_hi:[0,1]
	v_cvt_pk_bf16_f32 v138, v138, v139
	v_cvt_pk_bf16_f32 v139, v140, v141
	v_lshlrev_b32_e32 v140, 16, v148
	v_and_b32_e32 v141, 0xffff0000, v148
	v_pk_add_f32 v[140:141], v[142:143], v[140:141] neg_lo:[0,1] neg_hi:[0,1]
	v_lshlrev_b32_e32 v142, 16, v149
	v_and_b32_e32 v143, 0xffff0000, v149
	v_pk_add_f32 v[142:143], v[144:145], v[142:143] neg_lo:[0,1] neg_hi:[0,1]
	v_cvt_pk_bf16_f32 v140, v140, v141
	v_cvt_pk_bf16_f32 v141, v142, v143
	v_mfma_f32_16x16x32_bf16 v[100:103], v[146:149], v[4:7], v[100:103]
	v_mfma_f32_16x16x32_bf16 v[134:137], v[146:149], v[0:3], v[134:137]
	v_mfma_f32_16x16x32_bf16 v[138:141], v[138:141], v[0:3], v[100:103]
	s_nop 7
	v_pk_add_f32 v[102:103], v[134:135], v[138:139]
	v_lshlrev_b32_e32 v134, 16, v162
	v_fma_f32 v102, v79, v134, v102
	v_fmac_f32_e32 v103, v79, v131
	v_mul_f32_e32 v134, 0x3d372713, v102
	v_mul_f32_e32 v131, 0x3d372713, v103
	v_mul_f32_e32 v134, v102, v134
	v_mul_f32_e32 v131, v103, v131
	v_fma_f32 v134, v102, v134, v102
	v_fma_f32 v131, v103, v131, v103
	v_mul_f32_e32 v134, 0x3f4c422a, v134
	v_mul_f32_e32 v131, 0x3f4c422a, v131
	v_add_f32_e32 v134, v134, v134
	v_add_f32_e32 v131, v131, v131
	v_mul_f32_e32 v134, 0x3fb8aa3b, v134
	v_mul_f32_e32 v131, 0x3fb8aa3b, v131
	v_exp_f32_e32 v134, v134
	v_exp_f32_e32 v131, v131
	v_mul_f32_e32 v102, 0.5, v102
	v_mul_f32_e32 v103, 0.5, v103
	v_add_f32_e32 v134, 1.0, v134
	v_add_f32_e32 v131, 1.0, v131
	v_rcp_f32_e32 v134, v134
	v_rcp_f32_e32 v131, v131
	v_pk_add_f32 v[100:101], v[136:137], v[140:141]
	v_fma_f32 v134, v134, -2.0, 1.0
	v_fma_f32 v131, v131, -2.0, 1.0
	v_add_f32_e32 v134, 1.0, v134
	v_add_f32_e32 v131, 1.0, v131
	v_mul_f32_e32 v102, v102, v134
	v_mul_f32_e32 v103, v103, v131
	v_cvt_pk_bf16_f32 v134, v102, s0
	v_add_u32_e32 v102, s5, v114
	v_cvt_pk_bf16_f32 v103, v103, s0
	ds_write_b16 v102, v103 offset:1040
	s_waitcnt vmcnt(1)
; template <bool WRITEH>
; __device__ __forceinline__ void s5_block(const S5Coef& C, const bf16x8 (&bm)[8], u32x4 uw, float* Hs, int lane, float& hr, float& hi) {
;     const bf16x8 ua = __builtin_bit_cast(bf16x8, uw);
; #pragma unroll
;     for (int nb = 0; nb < 8; ++nb) { const f32x4 d = __builtin_amdgcn_mfma_f32_16x16x32_bf16(ua, bm[nb], (f32x4){0.f, 0.f, 0.f, 0.f}, 0, 0, 0);
; #pragma unroll
;         for (int i = 0; i < 4; ++i) Hs[(4 * (lane >> 4) + i) * 132 + 16 * nb + (lane & 15)] = d[i]; }
;     S5_LDS_FENCE();
;     float bur[16], bui[16];
; #pragma unroll
;     for (int tl = 0; tl < 16; ++tl) { bur[tl] = Hs[tl * 132 + lane]; bui[tl] = Hs[tl * 132 + 64 + lane]; }
; #pragma unroll
;     for (int tl = 0; tl < 16; ++tl) { const float nr = C.ar * hr - C.ai * hi + bur[tl], ni = C.ar * hi + C.ai * hr + bui[tl]; hr = nr; hi = ni; bur[tl] = hr; bui[tl] = hi; }
; __device__ __forceinline__ void s5_unit(ArgsP A, int l, int unit, unsigned char* lds, int wave_, int lane_) {
;     ...
;         for (int blk = 0; blk < 4; ++blk) {
;             unsigned short uraw[4];
; #pragma unroll
;             for (int i = 0; i < 4; ++i) uraw[i] = PROJ[(size_t)(rowbase + 16 * blk + 4 * (lane >> 4) + i) * INWP + C_S5 + 16 * g + (lane & 15)];
;             s5_block<true>(C, bm, uw[blk], Hs, lane, hr, hi);
;             f32x4 y = (f32x4){0.f, 0.f, 0.f, 0.f}, y2 = (f32x4){0.f, 0.f, 0.f, 0.f};
; #pragma unroll
;             for (int ks = 0; ks < 4; ++ks) { const float* hp = Hs + (lane & 15) * 132 + 32 * ks + 8 * (lane >> 4); const f32x4 h0 = *(const f32x4*)hp, h1 = *(const f32x4*)(hp + 4);
;                 u32x4 wh; wh.x = cvt_pk(h0[0], h0[1]); wh.y = cvt_pk(h0[2], h0[3]); wh.z = cvt_pk(h1[0], h1[1]); wh.w = cvt_pk(h1[2], h1[3]);
;                 u32x4 wl; wl.x = cvt_pk(h0[0] - bflo(wh.x), h0[1] - bfhi(wh.x)); wl.y = cvt_pk(h0[2] - bflo(wh.y), h0[3] - bfhi(wh.y)); wl.z = cvt_pk(h1[0] - bflo(wh.z), h1[1] - bfhi(wh.z)); wl.w = cvt_pk(h1[2] - bflo(wh.w), h1[3] - bfhi(wh.w));
;                 const bf16x8 hh_ = __builtin_bit_cast(bf16x8, wh), hl_ = __builtin_bit_cast(bf16x8, wl);
;                 y = __builtin_amdgcn_mfma_f32_16x16x32_bf16(hh_, chl[2 * ks], y, 0, 0, 0); y2 = __builtin_amdgcn_mfma_f32_16x16x32_bf16(hh_, chl[2 * ks + 1], y2, 0, 0, 0);
;                 y2 = __builtin_amdgcn_mfma_f32_16x16x32_bf16(hl_, chl[2 * ks], y2, 0, 0, 0); }
;             y = y + y2;
; #pragma unroll
	v_lshlrev_b32_e32 v103, 16, v130
	v_fma_f32 v100, v79, v103, v100
	v_mul_f32_e32 v103, 0x3d372713, v100
	v_mul_f32_e32 v103, v100, v103
	v_fma_f32 v103, v100, v103, v100
	v_mul_f32_e32 v103, 0x3f4c422a, v103
	v_add_f32_e32 v103, v103, v103
	v_mul_f32_e32 v103, 0x3fb8aa3b, v103
	v_exp_f32_e32 v103, v103
	v_mul_f32_e32 v100, 0.5, v100
	ds_write_b16 v102, v134
	v_mfma_f32_16x16x32_bf16 v[134:137], v[74:77], v[62:65], 0
	v_add_f32_e32 v103, 1.0, v103
	v_rcp_f32_e32 v103, v103
	s_add_i32 s5, s5, 32
	s_cmpk_lg_i32 s5, 0x80
	v_fma_f32 v103, v103, -2.0, 1.0
	v_add_f32_e32 v103, 1.0, v103
	v_mul_f32_e32 v100, v100, v103
	v_cvt_pk_bf16_f32 v100, v100, s0
	ds_write_b16 v102, v100 offset:2080
	s_waitcnt vmcnt(0)
	v_lshlrev_b32_e32 v100, 16, v129
	v_fmac_f32_e32 v101, v79, v100
	v_mul_f32_e32 v100, 0x3d372713, v101
	v_mul_f32_e32 v100, v101, v100
	v_fma_f32 v100, v101, v100, v101
	v_mul_f32_e32 v100, 0x3f4c422a, v100
	v_add_f32_e32 v100, v100, v100
	v_mul_f32_e32 v100, 0x3fb8aa3b, v100
	v_exp_f32_e32 v100, v100
	v_mul_f32_e32 v101, 0.5, v101
	v_add_f32_e32 v100, 1.0, v100
	v_rcp_f32_e32 v100, v100
	s_nop 0
	v_fma_f32 v100, v100, -2.0, 1.0
	v_add_f32_e32 v100, 1.0, v100
	v_mul_f32_e32 v100, v101, v100
	v_cvt_pk_bf16_f32 v100, v100, s0
	ds_write_b16 v102, v100 offset:3120
	s_waitcnt lgkmcnt(0)
	ds_write_b32 v106, v134
	ds_write_b32 v106, v135 offset:528
	ds_write_b32 v106, v136 offset:1056
	ds_write_b32 v107, v137
	v_mfma_f32_16x16x32_bf16 v[134:137], v[74:77], v[58:61], 0
	s_nop 7
	ds_write_b32 v106, v134 offset:64
	ds_write_b32 v106, v135 offset:592
	ds_write_b32 v106, v136 offset:1120
	ds_write_b32 v107, v137 offset:64
	v_mfma_f32_16x16x32_bf16 v[134:137], v[74:77], v[54:57], 0
	s_nop 7
	ds_write_b32 v106, v134 offset:128
	ds_write_b32 v106, v135 offset:656
	ds_write_b32 v106, v136 offset:1184
	ds_write_b32 v107, v137 offset:128
	v_mfma_f32_16x16x32_bf16 v[134:137], v[74:77], v[50:53], 0
	s_nop 7
	ds_write2_b32 v108, v134, v135 offset1:132
	ds_write_b32 v108, v136 offset:1056
	ds_write_b32 v109, v137
	v_mfma_f32_16x16x32_bf16 v[134:137], v[74:77], v[46:49], 0
	s_nop 7
	ds_write_b32 v106, v134 offset:256
	ds_write_b32 v106, v135 offset:784
	ds_write_b32 v106, v136 offset:1312
	ds_write_b32 v107, v137 offset:256
	v_mfma_f32_16x16x32_bf16 v[134:137], v[74:77], v[42:45], 0
	s_nop 7
	ds_write_b32 v106, v134 offset:320
	ds_write_b32 v106, v135 offset:848
	ds_write_b32 v106, v136 offset:1376
	ds_write_b32 v107, v137 offset:320
	v_mfma_f32_16x16x32_bf16 v[134:137], v[74:77], v[38:41], 0
	v_lshl_add_u64 v[100:101], s[2:3], 0, v[84:85]
	s_nop 6
	ds_write_b32 v106, v134 offset:384
	ds_write_b32 v106, v135 offset:912
	ds_write_b32 v106, v136 offset:1440
	ds_write_b32 v107, v137 offset:384
	v_mfma_f32_16x16x32_bf16 v[74:77], v[74:77], v[34:37], 0
	s_nop 7
	ds_write2_b32 v110, v74, v75 offset1:132
	ds_write_b32 v110, v76 offset:1056
	ds_write_b32 v111, v77
	v_add_co_u32_e32 v74, vcc, s12, v100
	v_lshl_add_u64 v[84:85], v[84:85], 0, 32
	s_nop 0
	v_addc_co_u32_e32 v75, vcc, 0, v101, vcc
	global_load_ushort v103, v[74:75], off
	v_add_co_u32_e32 v74, vcc, s13, v100
	s_waitcnt vmcnt(0)
	v_lshlrev_b32_e32 v103, 16, v103
	v_addc_co_u32_e32 v75, vcc, 0, v101, vcc
	global_load_ushort v129, v[74:75], off offset:512
	v_add_co_u32_e32 v74, vcc, s33, v100
	s_nop 1
	v_addc_co_u32_e32 v75, vcc, 0, v101, vcc
	global_load_ushort v158, v[74:75], off offset:1024
	v_add_co_u32_e32 v74, vcc, s28, v100
	s_nop 1
	v_addc_co_u32_e32 v75, vcc, 0, v101, vcc
	global_load_ushort v159, v[74:75], off offset:1536
	s_waitcnt lgkmcnt(0)
	ds_read2st64_b32 v[74:75], v112 offset1:1
	ds_read2_b32 v[76:77], v112 offset0:132 offset1:196
	ds_read2st64_b32 v[100:101], v115 offset0:4 offset1:5
	ds_read2st64_b32 v[130:131], v116 offset0:6 offset1:7
	ds_read2st64_b32 v[134:135], v117 offset0:8 offset1:9
	ds_read2st64_b32 v[136:137], v118 offset0:10 offset1:11
	ds_read2st64_b32 v[138:139], v119 offset0:12 offset1:13
	ds_read2st64_b32 v[140:141], v120 offset0:14 offset1:15
	ds_read2st64_b32 v[142:143], v121 offset0:16 offset1:17
	ds_read2st64_b32 v[144:145], v122 offset0:18 offset1:19
	ds_read2st64_b32 v[146:147], v123 offset0:20 offset1:21
	ds_read2st64_b32 v[148:149], v124 offset0:22 offset1:23
	ds_read2st64_b32 v[150:151], v125 offset0:24 offset1:25
	ds_read2st64_b32 v[152:153], v126 offset0:26 offset1:27
	ds_read2st64_b32 v[154:155], v127 offset0:28 offset1:29
	ds_read2st64_b32 v[156:157], v128 offset0:30 offset1:31
	s_waitcnt lgkmcnt(14)
	v_add_f32_e32 v160, v160, v74
	v_mul_f32_e32 v74, v32, v133
	v_fmac_f32_e32 v74, v33, v132
	v_add_f32_e32 v132, v74, v75
	v_mul_f32_e32 v74, v33, v132
	v_fma_f32 v74, v32, v160, -v74
	v_add_f32_e32 v76, v76, v74
	v_mul_f32_e32 v74, v32, v132
	v_fmac_f32_e32 v74, v33, v160
	v_add_f32_e32 v77, v77, v74
	v_mul_f32_e32 v74, v33, v77
	v_fma_f32 v74, v32, v76, -v74
	s_waitcnt lgkmcnt(13)
	v_add_f32_e32 v100, v100, v74
	v_mul_f32_e32 v74, v32, v77
	v_fmac_f32_e32 v74, v33, v76
	v_add_f32_e32 v101, v101, v74
	v_mul_f32_e32 v74, v33, v101
	v_fma_f32 v74, v32, v100, -v74
	s_waitcnt lgkmcnt(12)
	v_add_f32_e32 v130, v130, v74
	v_mul_f32_e32 v74, v32, v101
	v_fmac_f32_e32 v74, v33, v100
	v_add_f32_e32 v131, v131, v74
	v_mul_f32_e32 v74, v33, v131
	v_fma_f32 v74, v32, v130, -v74
	s_waitcnt lgkmcnt(11)
	v_add_f32_e32 v133, v134, v74
	v_mul_f32_e32 v74, v32, v131
	v_fmac_f32_e32 v74, v33, v130
	v_add_f32_e32 v134, v135, v74
	v_mul_f32_e32 v74, v33, v134
	v_fma_f32 v74, v32, v133, -v74
	s_waitcnt lgkmcnt(10)
	v_add_f32_e32 v135, v136, v74
	v_mul_f32_e32 v74, v32, v134
	v_fmac_f32_e32 v74, v33, v133
	v_add_f32_e32 v136, v137, v74
	v_mul_f32_e32 v74, v33, v136
	v_fma_f32 v74, v32, v135, -v74
	s_waitcnt lgkmcnt(9)
; __device__ __forceinline__ unsigned cvt_pk(float lo, float hi) { f32x2_t v = {lo, hi}; bf16x2_t b = __builtin_convertvector(v, bf16x2_t); return __builtin_bit_cast(unsigned, b); }
; __device__ __forceinline__ float bflo(unsigned w) { return __uint_as_float(w << 16); }
; __device__ __forceinline__ float bfhi(unsigned w) { return __uint_as_float(w & 0xffff0000u); }
; #define S5_LDS_FENCE() do { __builtin_amdgcn_wave_barrier(); asm volatile("s_waitcnt lgkmcnt(0)" ::: "memory"); } while (0)
; template <bool WRITEH>
; __device__ __forceinline__ void s5_block(const S5Coef& C, const bf16x8 (&bm)[8], u32x4 uw, float* Hs, int lane, float& hr, float& hi) {
;     ...
;     for (int tl = 0; tl < 16; ++tl) { bur[tl] = Hs[tl * 132 + lane]; bui[tl] = Hs[tl * 132 + 64 + lane]; }
; #pragma unroll
;     for (int tl = 0; tl < 16; ++tl) { const float nr = C.ar * hr - C.ai * hi + bur[tl], ni = C.ar * hi + C.ai * hr + bui[tl]; hr = nr; hi = ni; bur[tl] = hr; bui[tl] = hi; }
;     if (WRITEH) {
; #pragma unroll
;         for (int tl = 0; tl < 16; ++tl) { Hs[tl * 132 + lane] = bur[tl]; Hs[tl * 132 + 64 + lane] = bui[tl]; }
;     }
;     S5_LDS_FENCE();
; __device__ __forceinline__ void s5_unit(ArgsP A, int l, int unit, unsigned char* lds, int wave_, int lane_) {
;     ...
;             for (int ks = 0; ks < 4; ++ks) { const float* hp = Hs + (lane & 15) * 132 + 32 * ks + 8 * (lane >> 4); const f32x4 h0 = *(const f32x4*)hp, h1 = *(const f32x4*)(hp + 4);
;                 u32x4 wh; wh.x = cvt_pk(h0[0], h0[1]); wh.y = cvt_pk(h0[2], h0[3]); wh.z = cvt_pk(h1[0], h1[1]); wh.w = cvt_pk(h1[2], h1[3]);
;                 u32x4 wl; wl.x = cvt_pk(h0[0] - bflo(wh.x), h0[1] - bfhi(wh.x)); wl.y = cvt_pk(h0[2] - bflo(wh.y), h0[3] - bfhi(wh.y)); wl.z = cvt_pk(h1[0] - bflo(wh.z), h1[1] - bfhi(wh.z)); wl.w = cvt_pk(h1[2] - bflo(wh.w), h1[3] - bfhi(wh.w));
;                 const bf16x8 hh_ = __builtin_bit_cast(bf16x8, wh), hl_ = __builtin_bit_cast(bf16x8, wl);
;                 y = __builtin_amdgcn_mfma_f32_16x16x32_bf16(hh_, chl[2 * ks], y, 0, 0, 0); y2 = __builtin_amdgcn_mfma_f32_16x16x32_bf16(hh_, chl[2 * ks + 1], y2, 0, 0, 0);
;                 y2 = __builtin_amdgcn_mfma_f32_16x16x32_bf16(hl_, chl[2 * ks], y2, 0, 0, 0); }
	v_add_f32_e32 v137, v138, v74
	v_mul_f32_e32 v74, v32, v136
	v_fmac_f32_e32 v74, v33, v135
	v_add_f32_e32 v138, v139, v74
	v_mul_f32_e32 v74, v33, v138
	v_fma_f32 v74, v32, v137, -v74
	s_waitcnt lgkmcnt(8)
	v_add_f32_e32 v139, v140, v74
	v_mul_f32_e32 v74, v32, v138
	v_fmac_f32_e32 v74, v33, v137
	v_add_f32_e32 v140, v141, v74
	v_mul_f32_e32 v74, v33, v140
	v_fma_f32 v74, v32, v139, -v74
	s_waitcnt lgkmcnt(7)
	v_add_f32_e32 v141, v142, v74
	v_mul_f32_e32 v74, v32, v140
	v_fmac_f32_e32 v74, v33, v139
	v_add_f32_e32 v142, v143, v74
	v_mul_f32_e32 v74, v33, v142
	v_fma_f32 v74, v32, v141, -v74
	s_waitcnt lgkmcnt(6)
	v_add_f32_e32 v143, v144, v74
	v_mul_f32_e32 v74, v32, v142
	v_fmac_f32_e32 v74, v33, v141
	v_add_f32_e32 v144, v145, v74
	v_mul_f32_e32 v74, v33, v144
	v_fma_f32 v74, v32, v143, -v74
	s_waitcnt lgkmcnt(5)
	v_add_f32_e32 v145, v146, v74
	v_mul_f32_e32 v74, v32, v144
	v_fmac_f32_e32 v74, v33, v143
	v_add_f32_e32 v146, v147, v74
	v_mul_f32_e32 v74, v33, v146
	v_fma_f32 v74, v32, v145, -v74
	s_waitcnt lgkmcnt(4)
	v_add_f32_e32 v147, v148, v74
	v_mul_f32_e32 v74, v32, v146
	v_fmac_f32_e32 v74, v33, v145
	v_add_f32_e32 v148, v149, v74
	v_mul_f32_e32 v74, v33, v148
	v_fma_f32 v74, v32, v147, -v74
	s_waitcnt lgkmcnt(3)
	v_add_f32_e32 v149, v150, v74
	v_mul_f32_e32 v74, v32, v148
	v_fmac_f32_e32 v74, v33, v147
	v_add_f32_e32 v150, v151, v74
	v_mul_f32_e32 v74, v33, v150
	v_fma_f32 v74, v32, v149, -v74
	s_waitcnt lgkmcnt(2)
	v_add_f32_e32 v151, v152, v74
	v_mul_f32_e32 v74, v32, v150
	v_fmac_f32_e32 v74, v33, v149
	v_add_f32_e32 v152, v153, v74
	v_mul_f32_e32 v74, v33, v152
	v_fma_f32 v74, v32, v151, -v74
	s_waitcnt lgkmcnt(1)
	v_add_f32_e32 v153, v154, v74
	v_mul_f32_e32 v74, v32, v152
	v_fmac_f32_e32 v74, v33, v151
	v_add_f32_e32 v154, v155, v74
	v_mul_f32_e32 v74, v33, v154
	v_mul_f32_e32 v75, v32, v154
	v_fma_f32 v74, v32, v153, -v74
	v_fmac_f32_e32 v75, v33, v153
	s_waitcnt lgkmcnt(0)
	v_add_f32_e32 v74, v156, v74
	v_add_f32_e32 v75, v157, v75
	ds_write2st64_b32 v112, v160, v132 offset1:1
	ds_write2_b32 v112, v76, v77 offset0:132 offset1:196
	ds_write2st64_b32 v115, v100, v101 offset0:4 offset1:5
	ds_write2st64_b32 v116, v130, v131 offset0:6 offset1:7
	ds_write2st64_b32 v117, v133, v134 offset0:8 offset1:9
	ds_write2st64_b32 v118, v135, v136 offset0:10 offset1:11
	ds_write2st64_b32 v119, v137, v138 offset0:12 offset1:13
	ds_write2st64_b32 v120, v139, v140 offset0:14 offset1:15
	ds_write2st64_b32 v121, v141, v142 offset0:16 offset1:17
	ds_write2st64_b32 v122, v143, v144 offset0:18 offset1:19
	ds_write2st64_b32 v123, v145, v146 offset0:20 offset1:21
	ds_write2st64_b32 v124, v147, v148 offset0:22 offset1:23
	ds_write2st64_b32 v125, v149, v150 offset0:24 offset1:25
	ds_write2st64_b32 v126, v151, v152 offset0:26 offset1:27
	ds_write2st64_b32 v127, v153, v154 offset0:28 offset1:29
	ds_write2st64_b32 v128, v74, v75 offset0:30 offset1:31
	s_waitcnt lgkmcnt(0)
	ds_read_b128 v[130:133], v113
	ds_read_b128 v[134:137], v113 offset:16
	v_mul_f32_e32 v156, v33, v75
	v_fma_f32 v156, v32, v74, -v156
	s_waitcnt lgkmcnt(1)
	v_cvt_pk_bf16_f32 v138, v130, v131
	v_lshlrev_b32_e32 v76, 16, v138
	v_and_b32_e32 v77, 0xffff0000, v138
	v_cvt_pk_bf16_f32 v139, v132, v133
	v_pk_add_f32 v[76:77], v[130:131], v[76:77] neg_lo:[0,1] neg_hi:[0,1]
	s_waitcnt lgkmcnt(0)
	v_cvt_pk_bf16_f32 v140, v134, v135
	v_cvt_pk_bf16_f32 v130, v76, v77
	v_lshlrev_b32_e32 v76, 16, v139
	v_and_b32_e32 v77, 0xffff0000, v139
	v_pk_add_f32 v[76:77], v[132:133], v[76:77] neg_lo:[0,1] neg_hi:[0,1]
	v_cvt_pk_bf16_f32 v141, v136, v137
	v_cvt_pk_bf16_f32 v131, v76, v77
	v_lshlrev_b32_e32 v76, 16, v140
	v_and_b32_e32 v77, 0xffff0000, v140
	v_pk_add_f32 v[76:77], v[134:135], v[76:77] neg_lo:[0,1] neg_hi:[0,1]
	s_nop 0
	v_cvt_pk_bf16_f32 v132, v76, v77
	v_lshlrev_b32_e32 v76, 16, v141
	v_and_b32_e32 v77, 0xffff0000, v141
	v_pk_add_f32 v[76:77], v[136:137], v[76:77] neg_lo:[0,1] neg_hi:[0,1]
	v_mfma_f32_16x16x32_bf16 v[134:137], v[138:141], v[24:27], 0
	v_cvt_pk_bf16_f32 v133, v76, v77
	v_mfma_f32_16x16x32_bf16 v[138:141], v[138:141], v[28:31], 0
	s_nop 0
	v_mfma_f32_16x16x32_bf16 v[130:133], v[130:133], v[24:27], v[138:141]
	s_nop 5
	ds_read_b128 v[138:141], v113 offset:128
	ds_read_b128 v[142:145], v113 offset:144
	s_waitcnt lgkmcnt(1)
	v_cvt_pk_bf16_f32 v146, v138, v139
	v_lshlrev_b32_e32 v76, 16, v146
	v_and_b32_e32 v77, 0xffff0000, v146
	v_cvt_pk_bf16_f32 v147, v140, v141
	v_pk_add_f32 v[76:77], v[138:139], v[76:77] neg_lo:[0,1] neg_hi:[0,1]
	s_waitcnt lgkmcnt(0)
	v_cvt_pk_bf16_f32 v148, v142, v143
	v_cvt_pk_bf16_f32 v138, v76, v77
	v_lshlrev_b32_e32 v76, 16, v147
	v_and_b32_e32 v77, 0xffff0000, v147
	v_pk_add_f32 v[76:77], v[140:141], v[76:77] neg_lo:[0,1] neg_hi:[0,1]
	v_cvt_pk_bf16_f32 v149, v144, v145
	v_cvt_pk_bf16_f32 v139, v76, v77
	v_lshlrev_b32_e32 v76, 16, v148
	v_and_b32_e32 v77, 0xffff0000, v148
	v_pk_add_f32 v[76:77], v[142:143], v[76:77] neg_lo:[0,1] neg_hi:[0,1]
	v_mfma_f32_16x16x32_bf16 v[130:133], v[146:149], v[20:23], v[130:133]
	v_cvt_pk_bf16_f32 v140, v76, v77
	v_lshlrev_b32_e32 v76, 16, v149
	v_and_b32_e32 v77, 0xffff0000, v149
	v_pk_add_f32 v[76:77], v[144:145], v[76:77] neg_lo:[0,1] neg_hi:[0,1]
	v_mfma_f32_16x16x32_bf16 v[134:137], v[146:149], v[16:19], v[134:137]
	v_cvt_pk_bf16_f32 v141, v76, v77
	s_nop 1
	v_mfma_f32_16x16x32_bf16 v[130:133], v[138:141], v[16:19], v[130:133]
	ds_read_b128 v[138:141], v113 offset:256
	ds_read_b128 v[142:145], v113 offset:272
	s_waitcnt lgkmcnt(1)
	v_cvt_pk_bf16_f32 v146, v138, v139
	v_lshlrev_b32_e32 v76, 16, v146
	v_and_b32_e32 v77, 0xffff0000, v146
	v_cvt_pk_bf16_f32 v147, v140, v141
	v_pk_add_f32 v[76:77], v[138:139], v[76:77] neg_lo:[0,1] neg_hi:[0,1]
	s_waitcnt lgkmcnt(0)
; __device__ __forceinline__ unsigned cvt_pk(float lo, float hi) { f32x2_t v = {lo, hi}; bf16x2_t b = __builtin_convertvector(v, bf16x2_t); return __builtin_bit_cast(unsigned, b); }
; __device__ __forceinline__ float bf2f(unsigned short h) { return __uint_as_float(((unsigned)h) << 16); }
; __device__ __forceinline__ float bflo(unsigned w) { return __uint_as_float(w << 16); }
; __device__ __forceinline__ float bfhi(unsigned w) { return __uint_as_float(w & 0xffff0000u); }
; __device__ __forceinline__ unsigned short f2bf(float f) { return (unsigned short)(cvt_pk(f, 0.f) & 0xffffu); }
; __device__ __forceinline__ float fast_exp2(float x) { return __builtin_amdgcn_exp2f(x); }
; __device__ __forceinline__ float gelu_tanh(float x) {
;     const float z = 0.7978845608028654f * (x + 0.044715f * x * x * x);
;     const float e = fast_exp2(2.f * z * LOG2E);
;     const float th = 1.f - 2.f * fast_rcp(1.f + e);
;     return 0.5f * x * (1.f + th);
; }
; __device__ __forceinline__ void s5_unit(ArgsP A, int l, int unit, unsigned char* lds, int wave_, int lane_) {
;     ...
;             for (int ks = 0; ks < 4; ++ks) { const float* hp = Hs + (lane & 15) * 132 + 32 * ks + 8 * (lane >> 4); const f32x4 h0 = *(const f32x4*)hp, h1 = *(const f32x4*)(hp + 4);
;                 u32x4 wh; wh.x = cvt_pk(h0[0], h0[1]); wh.y = cvt_pk(h0[2], h0[3]); wh.z = cvt_pk(h1[0], h1[1]); wh.w = cvt_pk(h1[2], h1[3]);
;                 u32x4 wl; wl.x = cvt_pk(h0[0] - bflo(wh.x), h0[1] - bfhi(wh.x)); wl.y = cvt_pk(h0[2] - bflo(wh.y), h0[3] - bfhi(wh.y)); wl.z = cvt_pk(h1[0] - bflo(wh.z), h1[1] - bfhi(wh.z)); wl.w = cvt_pk(h1[2] - bflo(wh.w), h1[3] - bfhi(wh.w));
;                 const bf16x8 hh_ = __builtin_bit_cast(bf16x8, wh), hl_ = __builtin_bit_cast(bf16x8, wl);
;                 y = __builtin_amdgcn_mfma_f32_16x16x32_bf16(hh_, chl[2 * ks], y, 0, 0, 0); y2 = __builtin_amdgcn_mfma_f32_16x16x32_bf16(hh_, chl[2 * ks + 1], y2, 0, 0, 0);
;                 y2 = __builtin_amdgcn_mfma_f32_16x16x32_bf16(hl_, chl[2 * ks], y2, 0, 0, 0); }
;             y = y + y2;
; #pragma unroll
;             for (int i = 0; i < 4; ++i) { const int t = 16 * blk + 4 * (lane >> 4) + i; const int col = 16 * g + (lane & 15);
;                 const float uval = bf2f(uraw[i]); const float v = gelu_tanh(y[i] + dv * uval); ys[t * YS_STRIDE + col] = f2bf(v); }
	v_cvt_pk_bf16_f32 v148, v142, v143
	v_cvt_pk_bf16_f32 v138, v76, v77
	v_lshlrev_b32_e32 v76, 16, v147
	v_and_b32_e32 v77, 0xffff0000, v147
	v_pk_add_f32 v[76:77], v[140:141], v[76:77] neg_lo:[0,1] neg_hi:[0,1]
	v_cvt_pk_bf16_f32 v149, v144, v145
	v_cvt_pk_bf16_f32 v139, v76, v77
	v_lshlrev_b32_e32 v76, 16, v148
	v_and_b32_e32 v77, 0xffff0000, v148
	v_pk_add_f32 v[76:77], v[142:143], v[76:77] neg_lo:[0,1] neg_hi:[0,1]
	v_mfma_f32_16x16x32_bf16 v[130:133], v[146:149], v[12:15], v[130:133]
	v_cvt_pk_bf16_f32 v140, v76, v77
	v_lshlrev_b32_e32 v76, 16, v149
	v_and_b32_e32 v77, 0xffff0000, v149
	v_pk_add_f32 v[76:77], v[144:145], v[76:77] neg_lo:[0,1] neg_hi:[0,1]
	v_mfma_f32_16x16x32_bf16 v[134:137], v[146:149], v[8:11], v[134:137]
	v_cvt_pk_bf16_f32 v141, v76, v77
	s_nop 1
	v_mfma_f32_16x16x32_bf16 v[130:133], v[138:141], v[8:11], v[130:133]
	ds_read_b128 v[138:141], v113 offset:384
	ds_read_b128 v[142:145], v113 offset:400
	s_waitcnt lgkmcnt(1)
	v_cvt_pk_bf16_f32 v146, v138, v139
	v_lshlrev_b32_e32 v76, 16, v146
	v_and_b32_e32 v77, 0xffff0000, v146
	v_cvt_pk_bf16_f32 v147, v140, v141
	v_pk_add_f32 v[76:77], v[138:139], v[76:77] neg_lo:[0,1] neg_hi:[0,1]
	s_waitcnt lgkmcnt(0)
	v_cvt_pk_bf16_f32 v148, v142, v143
	v_cvt_pk_bf16_f32 v138, v76, v77
	v_lshlrev_b32_e32 v76, 16, v147
	v_and_b32_e32 v77, 0xffff0000, v147
	v_pk_add_f32 v[76:77], v[140:141], v[76:77] neg_lo:[0,1] neg_hi:[0,1]
	v_cvt_pk_bf16_f32 v149, v144, v145
	v_cvt_pk_bf16_f32 v139, v76, v77
	v_lshlrev_b32_e32 v76, 16, v148
	v_and_b32_e32 v77, 0xffff0000, v148
	v_pk_add_f32 v[76:77], v[142:143], v[76:77] neg_lo:[0,1] neg_hi:[0,1]
	v_mfma_f32_16x16x32_bf16 v[130:133], v[146:149], v[4:7], v[130:133]
	v_cvt_pk_bf16_f32 v140, v76, v77
	v_lshlrev_b32_e32 v76, 16, v149
	v_and_b32_e32 v77, 0xffff0000, v149
	v_pk_add_f32 v[76:77], v[144:145], v[76:77] neg_lo:[0,1] neg_hi:[0,1]
	v_mfma_f32_16x16x32_bf16 v[134:137], v[146:149], v[0:3], v[134:137]
	v_cvt_pk_bf16_f32 v141, v76, v77
	s_nop 1
	v_mfma_f32_16x16x32_bf16 v[130:133], v[138:141], v[0:3], v[130:133]
	s_nop 7
	v_pk_add_f32 v[100:101], v[134:135], v[130:131]
	v_pk_add_f32 v[76:77], v[136:137], v[132:133]
	v_fma_f32 v100, v79, v103, v100
	v_mul_f32_e32 v103, 0x3d372713, v100
	v_mul_f32_e32 v103, v100, v103
	v_fma_f32 v103, v100, v103, v100
	v_mul_f32_e32 v103, 0x3f4c422a, v103
	v_add_f32_e32 v103, v103, v103
	v_mul_f32_e32 v103, 0x3fb8aa3b, v103
	v_exp_f32_e32 v103, v103
	v_mul_f32_e32 v100, 0.5, v100
	v_mfma_f32_16x16x32_bf16 v[130:133], v[70:73], v[62:65], 0
	v_add_f32_e32 v103, 1.0, v103
	v_rcp_f32_e32 v103, v103
	v_mfma_f32_16x16x32_bf16 v[62:65], v[66:69], v[62:65], 0
	v_fma_f32 v103, v103, -2.0, 1.0
	v_add_f32_e32 v103, 1.0, v103
	v_mul_f32_e32 v100, v100, v103
	v_cvt_pk_bf16_f32 v100, v100, s0
	ds_write_b16 v102, v100 offset:16640
	s_waitcnt vmcnt(2)
	v_lshlrev_b32_e32 v100, 16, v129
	v_fmac_f32_e32 v101, v79, v100
	v_mul_f32_e32 v100, 0x3d372713, v101
	v_mul_f32_e32 v100, v101, v100
	v_fma_f32 v100, v101, v100, v101
	v_mul_f32_e32 v100, 0x3f4c422a, v100
	v_add_f32_e32 v100, v100, v100
	v_mul_f32_e32 v100, 0x3fb8aa3b, v100
	v_exp_f32_e32 v100, v100
	v_mul_f32_e32 v101, 0.5, v101
	v_add_f32_e32 v100, 1.0, v100
	v_rcp_f32_e32 v100, v100
	s_nop 0
	v_fma_f32 v100, v100, -2.0, 1.0
	v_add_f32_e32 v100, 1.0, v100
	v_mul_f32_e32 v100, v101, v100
	v_cvt_pk_bf16_f32 v100, v100, s0
	ds_write_b16 v102, v100 offset:17680
	s_waitcnt vmcnt(1)
	v_lshlrev_b32_e32 v100, 16, v158
	v_fma_f32 v76, v79, v100, v76
	v_mul_f32_e32 v100, 0x3d372713, v76
	v_mul_f32_e32 v100, v76, v100
	v_fma_f32 v100, v76, v100, v76
	v_mul_f32_e32 v100, 0x3f4c422a, v100
	v_add_f32_e32 v100, v100, v100
	v_mul_f32_e32 v100, 0x3fb8aa3b, v100
	v_exp_f32_e32 v100, v100
	v_mul_f32_e32 v76, 0.5, v76
	v_add_f32_e32 v100, 1.0, v100
	v_rcp_f32_e32 v100, v100
	s_nop 0
	v_fma_f32 v100, v100, -2.0, 1.0
	v_add_f32_e32 v100, 1.0, v100
	v_mul_f32_e32 v76, v76, v100
	v_cvt_pk_bf16_f32 v76, v76, s0
	ds_write_b16 v102, v76 offset:18720
	s_waitcnt vmcnt(0)
	v_lshlrev_b32_e32 v76, 16, v159
	v_fmac_f32_e32 v77, v79, v76
	v_mul_f32_e32 v76, 0x3d372713, v77
	v_mul_f32_e32 v76, v77, v76
	v_fma_f32 v76, v77, v76, v77
	v_mul_f32_e32 v76, 0x3f4c422a, v76
	v_add_f32_e32 v76, v76, v76
	v_mul_f32_e32 v76, 0x3fb8aa3b, v76
	v_exp_f32_e32 v76, v76
	v_mul_f32_e32 v77, 0.5, v77
	v_add_f32_e32 v76, 1.0, v76
	v_rcp_f32_e32 v76, v76
	s_nop 0
	v_fma_f32 v76, v76, -2.0, 1.0
	v_add_f32_e32 v76, 1.0, v76
	v_mul_f32_e32 v76, v77, v76
	v_cvt_pk_bf16_f32 v76, v76, s0
	ds_write_b16 v102, v76 offset:19760
	s_waitcnt lgkmcnt(0)
; #define S5_LDS_FENCE() do { __builtin_amdgcn_wave_barrier(); asm volatile("s_waitcnt lgkmcnt(0)" ::: "memory"); } while (0)
; template <bool WRITEH>
; __device__ __forceinline__ void s5_block(const S5Coef& C, const bf16x8 (&bm)[8], u32x4 uw, float* Hs, int lane, float& hr, float& hi) {
;     const bf16x8 ua = __builtin_bit_cast(bf16x8, uw);
; #pragma unroll
;     for (int nb = 0; nb < 8; ++nb) { const f32x4 d = __builtin_amdgcn_mfma_f32_16x16x32_bf16(ua, bm[nb], (f32x4){0.f, 0.f, 0.f, 0.f}, 0, 0, 0);
; #pragma unroll
;         for (int i = 0; i < 4; ++i) Hs[(4 * (lane >> 4) + i) * 132 + 16 * nb + (lane & 15)] = d[i]; }
;     S5_LDS_FENCE();
;     float bur[16], bui[16];
; #pragma unroll
;     for (int tl = 0; tl < 16; ++tl) { bur[tl] = Hs[tl * 132 + lane]; bui[tl] = Hs[tl * 132 + 64 + lane]; }
; #pragma unroll
;     for (int tl = 0; tl < 16; ++tl) { const float nr = C.ar * hr - C.ai * hi + bur[tl], ni = C.ar * hi + C.ai * hr + bui[tl]; hr = nr; hi = ni; bur[tl] = hr; bui[tl] = hi; }
; __device__ __forceinline__ void s5_unit(ArgsP A, int l, int unit, unsigned char* lds, int wave_, int lane_) {
;     ...
;         for (int blk = 0; blk < 4; ++blk) {
;             unsigned short uraw[4];
; #pragma unroll
;             for (int i = 0; i < 4; ++i) uraw[i] = PROJ[(size_t)(rowbase + 16 * blk + 4 * (lane >> 4) + i) * INWP + C_S5 + 16 * g + (lane & 15)];
;             s5_block<true>(C, bm, uw[blk], Hs, lane, hr, hi);
	ds_write_b32 v106, v130
	ds_write_b32 v106, v131 offset:528
	ds_write_b32 v106, v132 offset:1056
	ds_write_b32 v107, v133
	v_mfma_f32_16x16x32_bf16 v[130:133], v[70:73], v[58:61], 0
	s_nop 7
	ds_write_b32 v106, v130 offset:64
	ds_write_b32 v106, v131 offset:592
	ds_write_b32 v106, v132 offset:1120
	ds_write_b32 v107, v133 offset:64
	v_mfma_f32_16x16x32_bf16 v[130:133], v[70:73], v[54:57], 0
	s_nop 7
	ds_write_b32 v106, v130 offset:128
	ds_write_b32 v106, v131 offset:656
	ds_write_b32 v106, v132 offset:1184
	ds_write_b32 v107, v133 offset:128
	v_mfma_f32_16x16x32_bf16 v[130:133], v[70:73], v[50:53], 0
	s_nop 7
	ds_write2_b32 v108, v130, v131 offset1:132
	ds_write_b32 v108, v132 offset:1056
	ds_write_b32 v109, v133
	v_mfma_f32_16x16x32_bf16 v[130:133], v[70:73], v[46:49], 0
	s_nop 7
	ds_write_b32 v106, v130 offset:256
	ds_write_b32 v106, v131 offset:784
	ds_write_b32 v106, v132 offset:1312
	ds_write_b32 v107, v133 offset:256
	v_mfma_f32_16x16x32_bf16 v[130:133], v[70:73], v[42:45], 0
	s_nop 7
	ds_write_b32 v106, v130 offset:320
	ds_write_b32 v106, v131 offset:848
	ds_write_b32 v106, v132 offset:1376
	ds_write_b32 v107, v133 offset:320
	v_mfma_f32_16x16x32_bf16 v[130:133], v[70:73], v[38:41], 0
	v_lshl_add_u64 v[76:77], s[2:3], 0, v[82:83]
	s_nop 6
	ds_write_b32 v106, v130 offset:384
	ds_write_b32 v106, v131 offset:912
	ds_write_b32 v106, v132 offset:1440
	ds_write_b32 v107, v133 offset:384
	v_mfma_f32_16x16x32_bf16 v[70:73], v[70:73], v[34:37], 0
	s_nop 7
	ds_write2_b32 v110, v70, v71 offset1:132
	ds_write_b32 v110, v72 offset:1056
	ds_write_b32 v111, v73
	v_add_co_u32_e32 v70, vcc, s12, v76
	v_mfma_f32_16x16x32_bf16 v[58:61], v[66:69], v[58:61], 0
	s_nop 0
	v_addc_co_u32_e32 v71, vcc, 0, v77, vcc
	global_load_ushort v103, v[70:71], off
	v_add_co_u32_e32 v70, vcc, s13, v76
	v_mfma_f32_16x16x32_bf16 v[54:57], v[66:69], v[54:57], 0
	s_nop 0
	v_addc_co_u32_e32 v71, vcc, 0, v77, vcc
	global_load_ushort v129, v[70:71], off offset:512
	v_add_co_u32_e32 v70, vcc, s33, v76
	v_mfma_f32_16x16x32_bf16 v[50:53], v[66:69], v[50:53], 0
	s_nop 0
	v_addc_co_u32_e32 v71, vcc, 0, v77, vcc
	global_load_ushort v154, v[70:71], off offset:1024
	v_add_co_u32_e32 v70, vcc, s28, v76
	v_mfma_f32_16x16x32_bf16 v[46:49], v[66:69], v[46:49], 0
	s_nop 0
	v_addc_co_u32_e32 v71, vcc, 0, v77, vcc
	global_load_ushort v155, v[70:71], off offset:1536
	s_waitcnt lgkmcnt(0)
	ds_read2st64_b32 v[70:71], v112 offset1:1
	ds_read2_b32 v[72:73], v112 offset0:132 offset1:196
	ds_read2st64_b32 v[76:77], v115 offset0:4 offset1:5
	ds_read2st64_b32 v[100:101], v116 offset0:6 offset1:7
	ds_read2st64_b32 v[130:131], v117 offset0:8 offset1:9
	ds_read2st64_b32 v[132:133], v118 offset0:10 offset1:11
	ds_read2st64_b32 v[134:135], v119 offset0:12 offset1:13
	ds_read2st64_b32 v[136:137], v120 offset0:14 offset1:15
	ds_read2st64_b32 v[138:139], v121 offset0:16 offset1:17
	ds_read2st64_b32 v[140:141], v122 offset0:18 offset1:19
	ds_read2st64_b32 v[142:143], v123 offset0:20 offset1:21
	ds_read2st64_b32 v[144:145], v124 offset0:22 offset1:23
	ds_read2st64_b32 v[146:147], v125 offset0:24 offset1:25
	ds_read2st64_b32 v[148:149], v126 offset0:26 offset1:27
	ds_read2st64_b32 v[150:151], v127 offset0:28 offset1:29
	ds_read2st64_b32 v[152:153], v128 offset0:30 offset1:31
	s_waitcnt lgkmcnt(14)
	v_add_f32_e32 v156, v156, v70
	v_mul_f32_e32 v70, v32, v75
	v_fmac_f32_e32 v70, v33, v74
	v_add_f32_e32 v74, v70, v71
	v_mul_f32_e32 v70, v33, v74
	v_fma_f32 v70, v32, v156, -v70
	v_add_f32_e32 v72, v72, v70
	v_mul_f32_e32 v70, v32, v74
	v_fmac_f32_e32 v70, v33, v156
	v_add_f32_e32 v73, v73, v70
	v_mul_f32_e32 v70, v33, v73
	v_fma_f32 v70, v32, v72, -v70
	s_waitcnt lgkmcnt(13)
	v_add_f32_e32 v75, v76, v70
	v_mul_f32_e32 v70, v32, v73
	v_fmac_f32_e32 v70, v33, v72
	v_add_f32_e32 v76, v77, v70
	v_mul_f32_e32 v70, v33, v76
	v_fma_f32 v70, v32, v75, -v70
	s_waitcnt lgkmcnt(12)
	v_add_f32_e32 v77, v100, v70
	v_mul_f32_e32 v70, v32, v76
	v_fmac_f32_e32 v70, v33, v75
	v_add_f32_e32 v100, v101, v70
	v_mul_f32_e32 v70, v33, v100
	v_fma_f32 v70, v32, v77, -v70
	s_waitcnt lgkmcnt(11)
	v_add_f32_e32 v101, v130, v70
	v_mul_f32_e32 v70, v32, v100
	v_fmac_f32_e32 v70, v33, v77
	v_add_f32_e32 v130, v131, v70
	v_mul_f32_e32 v70, v33, v130
	v_fma_f32 v70, v32, v101, -v70
	s_waitcnt lgkmcnt(10)
	v_add_f32_e32 v131, v132, v70
	v_mul_f32_e32 v70, v32, v130
	v_fmac_f32_e32 v70, v33, v101
	v_add_f32_e32 v132, v133, v70
	v_mul_f32_e32 v70, v33, v132
	v_fma_f32 v70, v32, v131, -v70
	s_waitcnt lgkmcnt(9)
	v_add_f32_e32 v133, v134, v70
	v_mul_f32_e32 v70, v32, v132
	v_fmac_f32_e32 v70, v33, v131
	v_add_f32_e32 v134, v135, v70
	v_mul_f32_e32 v70, v33, v134
	v_fma_f32 v70, v32, v133, -v70
	s_waitcnt lgkmcnt(8)
	v_add_f32_e32 v135, v136, v70
	v_mul_f32_e32 v70, v32, v134
	v_fmac_f32_e32 v70, v33, v133
	v_add_f32_e32 v136, v137, v70
	v_mul_f32_e32 v70, v33, v136
	v_fma_f32 v70, v32, v135, -v70
	s_waitcnt lgkmcnt(7)
	v_add_f32_e32 v137, v138, v70
	v_mul_f32_e32 v70, v32, v136
	v_fmac_f32_e32 v70, v33, v135
	v_add_f32_e32 v138, v139, v70
	v_mul_f32_e32 v70, v33, v138
	v_fma_f32 v70, v32, v137, -v70
	s_waitcnt lgkmcnt(6)
	v_add_f32_e32 v139, v140, v70
	v_mul_f32_e32 v70, v32, v138
	v_fmac_f32_e32 v70, v33, v137
	v_add_f32_e32 v140, v141, v70
	v_mul_f32_e32 v70, v33, v140
	v_fma_f32 v70, v32, v139, -v70
	s_waitcnt lgkmcnt(5)
	v_add_f32_e32 v141, v142, v70
	v_mul_f32_e32 v70, v32, v140
	v_fmac_f32_e32 v70, v33, v139
	v_add_f32_e32 v142, v143, v70
	v_mul_f32_e32 v70, v33, v142
	v_fma_f32 v70, v32, v141, -v70
	s_waitcnt lgkmcnt(4)
	v_add_f32_e32 v143, v144, v70
	v_mul_f32_e32 v70, v32, v142
	v_fmac_f32_e32 v70, v33, v141
	v_add_f32_e32 v144, v145, v70
	v_mul_f32_e32 v70, v33, v144
	v_fma_f32 v70, v32, v143, -v70
	s_waitcnt lgkmcnt(3)
; __device__ __forceinline__ unsigned cvt_pk(float lo, float hi) { f32x2_t v = {lo, hi}; bf16x2_t b = __builtin_convertvector(v, bf16x2_t); return __builtin_bit_cast(unsigned, b); }
; __device__ __forceinline__ float bflo(unsigned w) { return __uint_as_float(w << 16); }
; __device__ __forceinline__ float bfhi(unsigned w) { return __uint_as_float(w & 0xffff0000u); }
; #define S5_LDS_FENCE() do { __builtin_amdgcn_wave_barrier(); asm volatile("s_waitcnt lgkmcnt(0)" ::: "memory"); } while (0)
; template <bool WRITEH>
; __device__ __forceinline__ void s5_block(const S5Coef& C, const bf16x8 (&bm)[8], u32x4 uw, float* Hs, int lane, float& hr, float& hi) {
;     ...
;     for (int tl = 0; tl < 16; ++tl) { bur[tl] = Hs[tl * 132 + lane]; bui[tl] = Hs[tl * 132 + 64 + lane]; }
; #pragma unroll
;     for (int tl = 0; tl < 16; ++tl) { const float nr = C.ar * hr - C.ai * hi + bur[tl], ni = C.ar * hi + C.ai * hr + bui[tl]; hr = nr; hi = ni; bur[tl] = hr; bui[tl] = hi; }
;     if (WRITEH) {
; #pragma unroll
;         for (int tl = 0; tl < 16; ++tl) { Hs[tl * 132 + lane] = bur[tl]; Hs[tl * 132 + 64 + lane] = bui[tl]; }
;     }
;     S5_LDS_FENCE();
; __device__ __forceinline__ void s5_unit(ArgsP A, int l, int unit, unsigned char* lds, int wave_, int lane_) {
;     ...
;             for (int ks = 0; ks < 4; ++ks) { const float* hp = Hs + (lane & 15) * 132 + 32 * ks + 8 * (lane >> 4); const f32x4 h0 = *(const f32x4*)hp, h1 = *(const f32x4*)(hp + 4);
;                 u32x4 wh; wh.x = cvt_pk(h0[0], h0[1]); wh.y = cvt_pk(h0[2], h0[3]); wh.z = cvt_pk(h1[0], h1[1]); wh.w = cvt_pk(h1[2], h1[3]);
;                 u32x4 wl; wl.x = cvt_pk(h0[0] - bflo(wh.x), h0[1] - bfhi(wh.x)); wl.y = cvt_pk(h0[2] - bflo(wh.y), h0[3] - bfhi(wh.y)); wl.z = cvt_pk(h1[0] - bflo(wh.z), h1[1] - bfhi(wh.z)); wl.w = cvt_pk(h1[2] - bflo(wh.w), h1[3] - bfhi(wh.w));
;                 const bf16x8 hh_ = __builtin_bit_cast(bf16x8, wh), hl_ = __builtin_bit_cast(bf16x8, wl);
;                 y = __builtin_amdgcn_mfma_f32_16x16x32_bf16(hh_, chl[2 * ks], y, 0, 0, 0); y2 = __builtin_amdgcn_mfma_f32_16x16x32_bf16(hh_, chl[2 * ks + 1], y2, 0, 0, 0);
;                 y2 = __builtin_amdgcn_mfma_f32_16x16x32_bf16(hl_, chl[2 * ks], y2, 0, 0, 0); }
	v_add_f32_e32 v145, v146, v70
	v_mul_f32_e32 v70, v32, v144
	v_fmac_f32_e32 v70, v33, v143
	v_add_f32_e32 v146, v147, v70
	v_mul_f32_e32 v70, v33, v146
	v_fma_f32 v70, v32, v145, -v70
	s_waitcnt lgkmcnt(2)
	v_add_f32_e32 v147, v148, v70
	v_mul_f32_e32 v70, v32, v146
	v_fmac_f32_e32 v70, v33, v145
	v_add_f32_e32 v148, v149, v70
	v_mul_f32_e32 v70, v33, v148
	v_fma_f32 v70, v32, v147, -v70
	s_waitcnt lgkmcnt(1)
	v_add_f32_e32 v149, v150, v70
	v_mul_f32_e32 v70, v32, v148
	v_fmac_f32_e32 v70, v33, v147
	v_add_f32_e32 v150, v151, v70
	v_mul_f32_e32 v70, v33, v150
	v_mul_f32_e32 v71, v32, v150
	v_fma_f32 v70, v32, v149, -v70
	v_fmac_f32_e32 v71, v33, v149
	s_waitcnt lgkmcnt(0)
	v_add_f32_e32 v70, v152, v70
	v_add_f32_e32 v71, v153, v71
	ds_write2st64_b32 v112, v156, v74 offset1:1
	ds_write2_b32 v112, v72, v73 offset0:132 offset1:196
	ds_write2st64_b32 v115, v75, v76 offset0:4 offset1:5
	ds_write2st64_b32 v116, v77, v100 offset0:6 offset1:7
	ds_write2st64_b32 v117, v101, v130 offset0:8 offset1:9
	ds_write2st64_b32 v118, v131, v132 offset0:10 offset1:11
	ds_write2st64_b32 v119, v133, v134 offset0:12 offset1:13
	ds_write2st64_b32 v120, v135, v136 offset0:14 offset1:15
	ds_write2st64_b32 v121, v137, v138 offset0:16 offset1:17
	ds_write2st64_b32 v122, v139, v140 offset0:18 offset1:19
	ds_write2st64_b32 v123, v141, v142 offset0:20 offset1:21
	ds_write2st64_b32 v124, v143, v144 offset0:22 offset1:23
	ds_write2st64_b32 v125, v145, v146 offset0:24 offset1:25
	ds_write2st64_b32 v126, v147, v148 offset0:26 offset1:27
	ds_write2st64_b32 v127, v149, v150 offset0:28 offset1:29
	ds_write2st64_b32 v128, v70, v71 offset0:30 offset1:31
	s_waitcnt lgkmcnt(0)
	ds_read_b128 v[72:75], v113
	ds_read_b128 v[130:133], v113 offset:16
	v_mfma_f32_16x16x32_bf16 v[42:45], v[66:69], v[42:45], 0
	v_lshl_add_u64 v[82:83], v[82:83], 0, 32
	s_waitcnt lgkmcnt(1)
	v_cvt_pk_bf16_f32 v134, v72, v73
	v_cvt_pk_bf16_f32 v135, v74, v75
	v_lshlrev_b32_e32 v76, 16, v134
	v_and_b32_e32 v77, 0xffff0000, v134
	s_waitcnt lgkmcnt(0)
	v_cvt_pk_bf16_f32 v136, v130, v131
	v_cvt_pk_bf16_f32 v137, v132, v133
	v_pk_add_f32 v[72:73], v[72:73], v[76:77] neg_lo:[0,1] neg_hi:[0,1]
	v_lshlrev_b32_e32 v76, 16, v135
	v_and_b32_e32 v77, 0xffff0000, v135
	v_pk_add_f32 v[74:75], v[74:75], v[76:77] neg_lo:[0,1] neg_hi:[0,1]
	v_cvt_pk_bf16_f32 v72, v72, v73
	v_cvt_pk_bf16_f32 v73, v74, v75
	v_lshlrev_b32_e32 v74, 16, v136
	v_and_b32_e32 v75, 0xffff0000, v136
	v_lshlrev_b32_e32 v76, 16, v137
	v_and_b32_e32 v77, 0xffff0000, v137
	v_pk_add_f32 v[74:75], v[130:131], v[74:75] neg_lo:[0,1] neg_hi:[0,1]
	v_pk_add_f32 v[76:77], v[132:133], v[76:77] neg_lo:[0,1] neg_hi:[0,1]
	v_cvt_pk_bf16_f32 v74, v74, v75
	v_cvt_pk_bf16_f32 v75, v76, v77
	v_mfma_f32_16x16x32_bf16 v[130:133], v[134:137], v[24:27], 0
	v_mfma_f32_16x16x32_bf16 v[134:137], v[134:137], v[28:31], 0
	v_mfma_f32_16x16x32_bf16 v[72:75], v[72:75], v[24:27], v[134:137]
	s_nop 6
	ds_read_b128 v[134:137], v113 offset:128
	ds_read_b128 v[138:141], v113 offset:144
	s_waitcnt lgkmcnt(1)
	v_cvt_pk_bf16_f32 v142, v134, v135
	v_lshlrev_b32_e32 v76, 16, v142
	v_and_b32_e32 v77, 0xffff0000, v142
	v_cvt_pk_bf16_f32 v143, v136, v137
	v_pk_add_f32 v[76:77], v[134:135], v[76:77] neg_lo:[0,1] neg_hi:[0,1]
	s_waitcnt lgkmcnt(0)
	v_cvt_pk_bf16_f32 v144, v138, v139
	v_cvt_pk_bf16_f32 v134, v76, v77
	v_lshlrev_b32_e32 v76, 16, v143
	v_and_b32_e32 v77, 0xffff0000, v143
	v_pk_add_f32 v[76:77], v[136:137], v[76:77] neg_lo:[0,1] neg_hi:[0,1]
	v_cvt_pk_bf16_f32 v145, v140, v141
	v_cvt_pk_bf16_f32 v135, v76, v77
	v_lshlrev_b32_e32 v76, 16, v144
	v_and_b32_e32 v77, 0xffff0000, v144
	v_pk_add_f32 v[76:77], v[138:139], v[76:77] neg_lo:[0,1] neg_hi:[0,1]
	v_mfma_f32_16x16x32_bf16 v[72:75], v[142:145], v[20:23], v[72:75]
	v_cvt_pk_bf16_f32 v136, v76, v77
	v_lshlrev_b32_e32 v76, 16, v145
	v_and_b32_e32 v77, 0xffff0000, v145
	v_pk_add_f32 v[76:77], v[140:141], v[76:77] neg_lo:[0,1] neg_hi:[0,1]
	v_mfma_f32_16x16x32_bf16 v[130:133], v[142:145], v[16:19], v[130:133]
	v_cvt_pk_bf16_f32 v137, v76, v77
	s_nop 1
	v_mfma_f32_16x16x32_bf16 v[72:75], v[134:137], v[16:19], v[72:75]
	ds_read_b128 v[134:137], v113 offset:256
	ds_read_b128 v[138:141], v113 offset:272
	s_waitcnt lgkmcnt(1)
	v_cvt_pk_bf16_f32 v142, v134, v135
	v_lshlrev_b32_e32 v76, 16, v142
	v_and_b32_e32 v77, 0xffff0000, v142
	v_cvt_pk_bf16_f32 v143, v136, v137
	v_pk_add_f32 v[76:77], v[134:135], v[76:77] neg_lo:[0,1] neg_hi:[0,1]
	s_waitcnt lgkmcnt(0)
	v_cvt_pk_bf16_f32 v144, v138, v139
	v_cvt_pk_bf16_f32 v134, v76, v77
	v_lshlrev_b32_e32 v76, 16, v143
	v_and_b32_e32 v77, 0xffff0000, v143
	v_pk_add_f32 v[76:77], v[136:137], v[76:77] neg_lo:[0,1] neg_hi:[0,1]
	v_cvt_pk_bf16_f32 v145, v140, v141
	v_cvt_pk_bf16_f32 v135, v76, v77
	v_lshlrev_b32_e32 v76, 16, v144
	v_and_b32_e32 v77, 0xffff0000, v144
	v_pk_add_f32 v[76:77], v[138:139], v[76:77] neg_lo:[0,1] neg_hi:[0,1]
	v_mfma_f32_16x16x32_bf16 v[72:75], v[142:145], v[12:15], v[72:75]
	v_cvt_pk_bf16_f32 v136, v76, v77
	v_lshlrev_b32_e32 v76, 16, v145
	v_and_b32_e32 v77, 0xffff0000, v145
	v_pk_add_f32 v[76:77], v[140:141], v[76:77] neg_lo:[0,1] neg_hi:[0,1]
	v_mfma_f32_16x16x32_bf16 v[130:133], v[142:145], v[8:11], v[130:133]
	v_cvt_pk_bf16_f32 v137, v76, v77
	s_nop 1
	v_mfma_f32_16x16x32_bf16 v[72:75], v[134:137], v[8:11], v[72:75]
	ds_read_b128 v[134:137], v113 offset:384
	ds_read_b128 v[138:141], v113 offset:400
	s_waitcnt lgkmcnt(1)
	v_cvt_pk_bf16_f32 v142, v134, v135
	v_lshlrev_b32_e32 v76, 16, v142
	v_and_b32_e32 v77, 0xffff0000, v142
	v_cvt_pk_bf16_f32 v143, v136, v137
	v_pk_add_f32 v[76:77], v[134:135], v[76:77] neg_lo:[0,1] neg_hi:[0,1]
	s_waitcnt lgkmcnt(0)
; __device__ __forceinline__ float bf2f(unsigned short h) { return __uint_as_float(((unsigned)h) << 16); }
; template <bool WRITEH>
; __device__ __forceinline__ void s5_block(const S5Coef& C, const bf16x8 (&bm)[8], u32x4 uw, float* Hs, int lane, float& hr, float& hi) {
;     const bf16x8 ua = __builtin_bit_cast(bf16x8, uw);
; #pragma unroll
;     for (int nb = 0; nb < 8; ++nb) { const f32x4 d = __builtin_amdgcn_mfma_f32_16x16x32_bf16(ua, bm[nb], (f32x4){0.f, 0.f, 0.f, 0.f}, 0, 0, 0);
; #pragma unroll
;         for (int i = 0; i < 4; ++i) Hs[(4 * (lane >> 4) + i) * 132 + 16 * nb + (lane & 15)] = d[i]; }
;     S5_LDS_FENCE();
;     float bur[16], bui[16];
; #pragma unroll
;     for (int tl = 0; tl < 16; ++tl) { bur[tl] = Hs[tl * 132 + lane]; bui[tl] = Hs[tl * 132 + 64 + lane]; }
; #pragma unroll
;     for (int tl = 0; tl < 16; ++tl) { const float nr = C.ar * hr - C.ai * hi + bur[tl], ni = C.ar * hi + C.ai * hr + bui[tl]; hr = nr; hi = ni; bur[tl] = hr; bui[tl] = hi; }
; __device__ __forceinline__ void s5_unit(ArgsP A, int l, int unit, unsigned char* lds, int wave_, int lane_) {
;     ...
;             for (int ks = 0; ks < 4; ++ks) { const float* hp = Hs + (lane & 15) * 132 + 32 * ks + 8 * (lane >> 4); const f32x4 h0 = *(const f32x4*)hp, h1 = *(const f32x4*)(hp + 4);
;                 u32x4 wh; wh.x = cvt_pk(h0[0], h0[1]); wh.y = cvt_pk(h0[2], h0[3]); wh.z = cvt_pk(h1[0], h1[1]); wh.w = cvt_pk(h1[2], h1[3]);
;                 u32x4 wl; wl.x = cvt_pk(h0[0] - bflo(wh.x), h0[1] - bfhi(wh.x)); wl.y = cvt_pk(h0[2] - bflo(wh.y), h0[3] - bfhi(wh.y)); wl.z = cvt_pk(h1[0] - bflo(wh.z), h1[1] - bfhi(wh.z)); wl.w = cvt_pk(h1[2] - bflo(wh.w), h1[3] - bfhi(wh.w));
;                 const bf16x8 hh_ = __builtin_bit_cast(bf16x8, wh), hl_ = __builtin_bit_cast(bf16x8, wl);
;                 y = __builtin_amdgcn_mfma_f32_16x16x32_bf16(hh_, chl[2 * ks], y, 0, 0, 0); y2 = __builtin_amdgcn_mfma_f32_16x16x32_bf16(hh_, chl[2 * ks + 1], y2, 0, 0, 0);
;                 y2 = __builtin_amdgcn_mfma_f32_16x16x32_bf16(hl_, chl[2 * ks], y2, 0, 0, 0); }
;             y = y + y2;
; #pragma unroll
;             for (int i = 0; i < 4; ++i) { const int t = 16 * blk + 4 * (lane >> 4) + i; const int col = 16 * g + (lane & 15);
;                 const float uval = bf2f(uraw[i]); const float v = gelu_tanh(y[i] + dv * uval); ys[t * YS_STRIDE + col] = f2bf(v); }
	v_cvt_pk_bf16_f32 v144, v138, v139
	v_cvt_pk_bf16_f32 v134, v76, v77
	v_lshlrev_b32_e32 v76, 16, v143
	v_and_b32_e32 v77, 0xffff0000, v143
	v_pk_add_f32 v[76:77], v[136:137], v[76:77] neg_lo:[0,1] neg_hi:[0,1]
	v_cvt_pk_bf16_f32 v145, v140, v141
	v_cvt_pk_bf16_f32 v135, v76, v77
	v_lshlrev_b32_e32 v76, 16, v144
	v_and_b32_e32 v77, 0xffff0000, v144
	v_pk_add_f32 v[76:77], v[138:139], v[76:77] neg_lo:[0,1] neg_hi:[0,1]
	v_mfma_f32_16x16x32_bf16 v[72:75], v[142:145], v[4:7], v[72:75]
	v_cvt_pk_bf16_f32 v136, v76, v77
	v_lshlrev_b32_e32 v76, 16, v145
	v_and_b32_e32 v77, 0xffff0000, v145
	v_pk_add_f32 v[76:77], v[140:141], v[76:77] neg_lo:[0,1] neg_hi:[0,1]
	v_mfma_f32_16x16x32_bf16 v[130:133], v[142:145], v[0:3], v[130:133]
	v_cvt_pk_bf16_f32 v137, v76, v77
	s_waitcnt vmcnt(3)
	v_lshlrev_b32_e32 v76, 16, v103
	v_mfma_f32_16x16x32_bf16 v[72:75], v[134:137], v[0:3], v[72:75]
	v_mfma_f32_16x16x32_bf16 v[38:41], v[66:69], v[38:41], 0
	s_nop 6
	v_add_f32_e64 v72, v130, v72
	v_add_f32_e64 v73, v131, v73
	v_pk_add_f32 v[74:75], v[132:133], v[74:75]
	v_fma_f32 v72, v79, v76, v72
	v_mul_f32_e32 v76, 0x3d372713, v72
	v_mul_f32_e32 v76, v72, v76
	v_fma_f32 v76, v72, v76, v72
	v_mul_f32_e32 v76, 0x3f4c422a, v76
	v_add_f32_e32 v76, v76, v76
	v_mul_f32_e32 v76, 0x3fb8aa3b, v76
	v_exp_f32_e32 v76, v76
	v_mul_f32_e32 v72, 0.5, v72
	v_mfma_f32_16x16x32_bf16 v[34:37], v[66:69], v[34:37], 0
	v_add_f32_e32 v76, 1.0, v76
	v_rcp_f32_e32 v76, v76
	s_nop 0
	v_fma_f32 v76, v76, -2.0, 1.0
	v_add_f32_e32 v76, 1.0, v76
	v_mul_f32_e32 v72, v72, v76
	v_cvt_pk_bf16_f32 v72, v72, s0
	ds_write_b16 v102, v72 offset:33280
	s_waitcnt vmcnt(2)
	v_lshlrev_b32_e32 v72, 16, v129
	v_fmac_f32_e32 v73, v79, v72
	v_mul_f32_e32 v72, 0x3d372713, v73
	v_mul_f32_e32 v72, v73, v72
	v_fma_f32 v72, v73, v72, v73
	v_mul_f32_e32 v72, 0x3f4c422a, v72
	v_add_f32_e32 v72, v72, v72
	v_mul_f32_e32 v72, 0x3fb8aa3b, v72
	v_exp_f32_e32 v72, v72
	v_mul_f32_e32 v73, 0.5, v73
	v_add_f32_e32 v72, 1.0, v72
	v_rcp_f32_e32 v72, v72
	s_nop 0
	v_fma_f32 v72, v72, -2.0, 1.0
	v_add_f32_e32 v72, 1.0, v72
	v_mul_f32_e32 v72, v73, v72
	v_cvt_pk_bf16_f32 v72, v72, s0
	ds_write_b16 v102, v72 offset:34320
	s_waitcnt vmcnt(1)
	v_lshlrev_b32_e32 v72, 16, v154
	v_fma_f32 v72, v79, v72, v74
	v_mul_f32_e32 v73, 0x3d372713, v72
	v_mul_f32_e32 v73, v72, v73
	v_fma_f32 v73, v72, v73, v72
	v_mul_f32_e32 v73, 0x3f4c422a, v73
	v_add_f32_e32 v73, v73, v73
	v_mul_f32_e32 v73, 0x3fb8aa3b, v73
	v_exp_f32_e32 v73, v73
	v_mul_f32_e32 v72, 0.5, v72
	v_add_f32_e32 v73, 1.0, v73
	v_rcp_f32_e32 v73, v73
	s_nop 0
	v_fma_f32 v73, v73, -2.0, 1.0
	v_add_f32_e32 v73, 1.0, v73
	v_mul_f32_e32 v72, v72, v73
	v_cvt_pk_bf16_f32 v72, v72, s0
	ds_write_b16 v102, v72 offset:35360
	s_waitcnt vmcnt(0)
	v_lshlrev_b32_e32 v72, 16, v155
	v_fmac_f32_e32 v75, v79, v72
	v_mul_f32_e32 v72, 0x3d372713, v75
	v_mul_f32_e32 v72, v75, v72
	v_fma_f32 v72, v75, v72, v75
	v_mul_f32_e32 v72, 0x3f4c422a, v72
	v_add_f32_e32 v72, v72, v72
	v_mul_f32_e32 v72, 0x3fb8aa3b, v72
	v_exp_f32_e32 v72, v72
	v_mul_f32_e32 v73, 0.5, v75
	v_add_f32_e32 v72, 1.0, v72
	v_rcp_f32_e32 v72, v72
	s_nop 0
	v_fma_f32 v72, v72, -2.0, 1.0
	v_add_f32_e32 v72, 1.0, v72
	v_mul_f32_e32 v72, v73, v72
	v_cvt_pk_bf16_f32 v72, v72, s0
	ds_write_b16 v102, v72 offset:36400
	v_lshl_add_u64 v[72:73], s[2:3], 0, v[80:81]
	s_waitcnt lgkmcnt(0)
	ds_write_b32 v106, v62
	ds_write_b32 v106, v63 offset:528
	ds_write_b32 v106, v64 offset:1056
	ds_write_b32 v107, v65
	ds_write_b32 v106, v58 offset:64
	ds_write_b32 v106, v59 offset:592
	ds_write_b32 v106, v60 offset:1120
	ds_write_b32 v107, v61 offset:64
	ds_write_b32 v106, v54 offset:128
	ds_write_b32 v106, v55 offset:656
	ds_write_b32 v106, v56 offset:1184
	ds_write_b32 v107, v57 offset:128
	ds_write2_b32 v108, v50, v51 offset1:132
	ds_write_b32 v108, v52 offset:1056
	ds_write_b32 v109, v53
	ds_write_b32 v106, v46 offset:256
	ds_write_b32 v106, v47 offset:784
	ds_write_b32 v106, v48 offset:1312
	ds_write_b32 v107, v49 offset:256
	ds_write_b32 v106, v42 offset:320
	ds_write_b32 v106, v43 offset:848
	ds_write_b32 v106, v44 offset:1376
	ds_write_b32 v107, v45 offset:320
	ds_write_b32 v106, v38 offset:384
	ds_write_b32 v106, v39 offset:912
	ds_write_b32 v106, v40 offset:1440
	ds_write_b32 v107, v41 offset:384
	ds_write2_b32 v110, v34, v35 offset1:132
	ds_write_b32 v110, v36 offset:1056
	ds_write_b32 v111, v37
	v_add_co_u32_e32 v34, vcc, s12, v72
	v_lshl_add_u64 v[80:81], v[80:81], 0, 32
	s_nop 0
	v_addc_co_u32_e32 v35, vcc, 0, v73, vcc
	global_load_ushort v66, v[34:35], off
	v_add_co_u32_e32 v34, vcc, s13, v72
	s_nop 1
	v_addc_co_u32_e32 v35, vcc, 0, v73, vcc
	global_load_ushort v67, v[34:35], off offset:512
	v_add_co_u32_e32 v34, vcc, s33, v72
	s_nop 1
	v_addc_co_u32_e32 v35, vcc, 0, v73, vcc
	global_load_ushort v68, v[34:35], off offset:1024
	v_add_co_u32_e32 v34, vcc, s28, v72
	v_mul_f32_e32 v72, v33, v71
	s_nop 0
	v_addc_co_u32_e32 v35, vcc, 0, v73, vcc
	global_load_ushort v69, v[34:35], off offset:1536
	s_waitcnt lgkmcnt(0)
	v_mul_f32_e32 v71, v32, v71
	ds_read2st64_b32 v[34:35], v112 offset1:1
	ds_read2_b32 v[36:37], v112 offset0:132 offset1:196
	ds_read2st64_b32 v[38:39], v115 offset0:4 offset1:5
	ds_read2st64_b32 v[40:41], v116 offset0:6 offset1:7
	ds_read2st64_b32 v[42:43], v117 offset0:8 offset1:9
	ds_read2st64_b32 v[44:45], v118 offset0:10 offset1:11
	ds_read2st64_b32 v[46:47], v119 offset0:12 offset1:13
	ds_read2st64_b32 v[48:49], v120 offset0:14 offset1:15
	ds_read2st64_b32 v[50:51], v121 offset0:16 offset1:17
	ds_read2st64_b32 v[52:53], v122 offset0:18 offset1:19
	ds_read2st64_b32 v[54:55], v123 offset0:20 offset1:21
	ds_read2st64_b32 v[56:57], v124 offset0:22 offset1:23
	ds_read2st64_b32 v[58:59], v125 offset0:24 offset1:25
	ds_read2st64_b32 v[60:61], v126 offset0:26 offset1:27
	ds_read2st64_b32 v[62:63], v127 offset0:28 offset1:29
	ds_read2st64_b32 v[64:65], v128 offset0:30 offset1:31
	v_fmac_f32_e32 v71, v33, v70
	v_fma_f32 v72, v32, v70, -v72
	s_waitcnt lgkmcnt(14)
; __device__ __forceinline__ unsigned cvt_pk(float lo, float hi) { f32x2_t v = {lo, hi}; bf16x2_t b = __builtin_convertvector(v, bf16x2_t); return __builtin_bit_cast(unsigned, b); }
; __device__ __forceinline__ float bflo(unsigned w) { return __uint_as_float(w << 16); }
; __device__ __forceinline__ float bfhi(unsigned w) { return __uint_as_float(w & 0xffff0000u); }
; #define S5_LDS_FENCE() do { __builtin_amdgcn_wave_barrier(); asm volatile("s_waitcnt lgkmcnt(0)" ::: "memory"); } while (0)
; template <bool WRITEH>
; __device__ __forceinline__ void s5_block(const S5Coef& C, const bf16x8 (&bm)[8], u32x4 uw, float* Hs, int lane, float& hr, float& hi) {
;     ...
;     for (int tl = 0; tl < 16; ++tl) { bur[tl] = Hs[tl * 132 + lane]; bui[tl] = Hs[tl * 132 + 64 + lane]; }
; #pragma unroll
;     for (int tl = 0; tl < 16; ++tl) { const float nr = C.ar * hr - C.ai * hi + bur[tl], ni = C.ar * hi + C.ai * hr + bui[tl]; hr = nr; hi = ni; bur[tl] = hr; bui[tl] = hi; }
;     if (WRITEH) {
; #pragma unroll
;         for (int tl = 0; tl < 16; ++tl) { Hs[tl * 132 + lane] = bur[tl]; Hs[tl * 132 + 64 + lane] = bui[tl]; }
;     }
;     S5_LDS_FENCE();
; __device__ __forceinline__ void s5_unit(ArgsP A, int l, int unit, unsigned char* lds, int wave_, int lane_) {
;     ...
;             for (int ks = 0; ks < 4; ++ks) { const float* hp = Hs + (lane & 15) * 132 + 32 * ks + 8 * (lane >> 4); const f32x4 h0 = *(const f32x4*)hp, h1 = *(const f32x4*)(hp + 4);
;                 u32x4 wh; wh.x = cvt_pk(h0[0], h0[1]); wh.y = cvt_pk(h0[2], h0[3]); wh.z = cvt_pk(h1[0], h1[1]); wh.w = cvt_pk(h1[2], h1[3]);
;                 u32x4 wl; wl.x = cvt_pk(h0[0] - bflo(wh.x), h0[1] - bfhi(wh.x)); wl.y = cvt_pk(h0[2] - bflo(wh.y), h0[3] - bfhi(wh.y)); wl.z = cvt_pk(h1[0] - bflo(wh.z), h1[1] - bfhi(wh.z)); wl.w = cvt_pk(h1[2] - bflo(wh.w), h1[3] - bfhi(wh.w));
;                 const bf16x8 hh_ = __builtin_bit_cast(bf16x8, wh), hl_ = __builtin_bit_cast(bf16x8, wl);
;                 y = __builtin_amdgcn_mfma_f32_16x16x32_bf16(hh_, chl[2 * ks], y, 0, 0, 0); y2 = __builtin_amdgcn_mfma_f32_16x16x32_bf16(hh_, chl[2 * ks + 1], y2, 0, 0, 0);
;                 y2 = __builtin_amdgcn_mfma_f32_16x16x32_bf16(hl_, chl[2 * ks], y2, 0, 0, 0); }
	v_add_f32_e32 v35, v71, v35
	v_add_f32_e32 v34, v72, v34
	v_mul_f32_e32 v70, v33, v35
	v_fma_f32 v70, v32, v34, -v70
	v_add_f32_e32 v36, v36, v70
	v_mul_f32_e32 v70, v32, v35
	v_fmac_f32_e32 v70, v33, v34
	v_add_f32_e32 v37, v37, v70
	v_mul_f32_e32 v70, v33, v37
	v_fma_f32 v70, v32, v36, -v70
	s_waitcnt lgkmcnt(13)
	v_add_f32_e32 v38, v38, v70
	v_mul_f32_e32 v70, v32, v37
	v_fmac_f32_e32 v70, v33, v36
	v_add_f32_e32 v39, v39, v70
	v_mul_f32_e32 v70, v33, v39
	v_fma_f32 v70, v32, v38, -v70
	s_waitcnt lgkmcnt(12)
	v_add_f32_e32 v40, v40, v70
	v_mul_f32_e32 v70, v32, v39
	v_fmac_f32_e32 v70, v33, v38
	v_add_f32_e32 v41, v41, v70
	v_mul_f32_e32 v70, v33, v41
	v_fma_f32 v70, v32, v40, -v70
	s_waitcnt lgkmcnt(11)
	v_add_f32_e32 v42, v42, v70
	v_mul_f32_e32 v70, v32, v41
	v_fmac_f32_e32 v70, v33, v40
	v_add_f32_e32 v43, v43, v70
	v_mul_f32_e32 v70, v33, v43
	v_fma_f32 v70, v32, v42, -v70
	s_waitcnt lgkmcnt(10)
	v_add_f32_e32 v44, v44, v70
	v_mul_f32_e32 v70, v32, v43
	v_fmac_f32_e32 v70, v33, v42
	v_add_f32_e32 v45, v45, v70
	v_mul_f32_e32 v70, v33, v45
	v_fma_f32 v70, v32, v44, -v70
	s_waitcnt lgkmcnt(9)
	v_add_f32_e32 v46, v46, v70
	v_mul_f32_e32 v70, v32, v45
	v_fmac_f32_e32 v70, v33, v44
	v_add_f32_e32 v47, v47, v70
	v_mul_f32_e32 v70, v33, v47
	v_fma_f32 v70, v32, v46, -v70
	s_waitcnt lgkmcnt(8)
	v_add_f32_e32 v48, v48, v70
	v_mul_f32_e32 v70, v32, v47
	v_fmac_f32_e32 v70, v33, v46
	v_add_f32_e32 v49, v49, v70
	v_mul_f32_e32 v70, v33, v49
	v_fma_f32 v70, v32, v48, -v70
	s_waitcnt lgkmcnt(7)
	v_add_f32_e32 v50, v50, v70
	v_mul_f32_e32 v70, v32, v49
	v_fmac_f32_e32 v70, v33, v48
	v_add_f32_e32 v51, v51, v70
	v_mul_f32_e32 v70, v33, v51
	v_fma_f32 v70, v32, v50, -v70
	s_waitcnt lgkmcnt(6)
	v_add_f32_e32 v52, v52, v70
	v_mul_f32_e32 v70, v32, v51
	v_fmac_f32_e32 v70, v33, v50
	v_add_f32_e32 v53, v53, v70
	v_mul_f32_e32 v70, v33, v53
	v_fma_f32 v70, v32, v52, -v70
	s_waitcnt lgkmcnt(5)
	v_add_f32_e32 v54, v54, v70
	v_mul_f32_e32 v70, v32, v53
	v_fmac_f32_e32 v70, v33, v52
	v_add_f32_e32 v55, v55, v70
	v_mul_f32_e32 v70, v33, v55
	v_fma_f32 v70, v32, v54, -v70
	s_waitcnt lgkmcnt(4)
	v_add_f32_e32 v56, v56, v70
	v_mul_f32_e32 v70, v32, v55
	v_fmac_f32_e32 v70, v33, v54
	v_add_f32_e32 v57, v57, v70
	v_mul_f32_e32 v70, v33, v57
	v_fma_f32 v70, v32, v56, -v70
	s_waitcnt lgkmcnt(3)
	v_add_f32_e32 v58, v58, v70
	v_mul_f32_e32 v70, v32, v57
	v_fmac_f32_e32 v70, v33, v56
	v_add_f32_e32 v59, v59, v70
	v_mul_f32_e32 v70, v33, v59
	v_fma_f32 v70, v32, v58, -v70
	s_waitcnt lgkmcnt(2)
	v_add_f32_e32 v60, v60, v70
	v_mul_f32_e32 v70, v32, v59
	v_fmac_f32_e32 v70, v33, v58
	v_add_f32_e32 v61, v61, v70
	v_mul_f32_e32 v70, v33, v61
	v_fma_f32 v70, v32, v60, -v70
	s_waitcnt lgkmcnt(1)
	v_add_f32_e32 v62, v62, v70
	v_mul_f32_e32 v70, v32, v61
	v_fmac_f32_e32 v70, v33, v60
	v_add_f32_e32 v63, v63, v70
	v_mul_f32_e32 v70, v33, v63
	v_fma_f32 v70, v32, v62, -v70
	v_mul_f32_e32 v32, v32, v63
	v_fmac_f32_e32 v32, v33, v62
	s_waitcnt lgkmcnt(0)
	v_add_f32_e32 v64, v64, v70
	v_add_f32_e32 v32, v65, v32
	ds_write2st64_b32 v112, v34, v35 offset1:1
	ds_write2_b32 v112, v36, v37 offset0:132 offset1:196
	ds_write2st64_b32 v115, v38, v39 offset0:4 offset1:5
	ds_write2st64_b32 v116, v40, v41 offset0:6 offset1:7
	ds_write2st64_b32 v117, v42, v43 offset0:8 offset1:9
	ds_write2st64_b32 v118, v44, v45 offset0:10 offset1:11
	ds_write2st64_b32 v119, v46, v47 offset0:12 offset1:13
	ds_write2st64_b32 v120, v48, v49 offset0:14 offset1:15
	ds_write2st64_b32 v121, v50, v51 offset0:16 offset1:17
	ds_write2st64_b32 v122, v52, v53 offset0:18 offset1:19
	ds_write2st64_b32 v123, v54, v55 offset0:20 offset1:21
	ds_write2st64_b32 v124, v56, v57 offset0:22 offset1:23
	ds_write2st64_b32 v125, v58, v59 offset0:24 offset1:25
	ds_write2st64_b32 v126, v60, v61 offset0:26 offset1:27
	ds_write2st64_b32 v127, v62, v63 offset0:28 offset1:29
	ds_write2st64_b32 v128, v64, v32 offset0:30 offset1:31
	s_waitcnt lgkmcnt(0)
	ds_read_b128 v[32:35], v113
	ds_read_b128 v[36:39], v113 offset:16
	s_waitcnt lgkmcnt(1)
	v_cvt_pk_bf16_f32 v40, v32, v33
	v_cvt_pk_bf16_f32 v41, v34, v35
	v_lshlrev_b32_e32 v44, 16, v40
	v_and_b32_e32 v45, 0xffff0000, v40
	v_pk_add_f32 v[32:33], v[32:33], v[44:45] neg_lo:[0,1] neg_hi:[0,1]
	v_lshlrev_b32_e32 v44, 16, v41
	v_and_b32_e32 v45, 0xffff0000, v41
	s_waitcnt lgkmcnt(0)
	v_cvt_pk_bf16_f32 v42, v36, v37
	v_cvt_pk_bf16_f32 v43, v38, v39
	v_pk_add_f32 v[34:35], v[34:35], v[44:45] neg_lo:[0,1] neg_hi:[0,1]
	v_cvt_pk_bf16_f32 v32, v32, v33
	v_cvt_pk_bf16_f32 v33, v34, v35
	v_lshlrev_b32_e32 v34, 16, v42
	v_and_b32_e32 v35, 0xffff0000, v42
	v_pk_add_f32 v[34:35], v[36:37], v[34:35] neg_lo:[0,1] neg_hi:[0,1]
	v_lshlrev_b32_e32 v36, 16, v43
	v_and_b32_e32 v37, 0xffff0000, v43
	v_pk_add_f32 v[36:37], v[38:39], v[36:37] neg_lo:[0,1] neg_hi:[0,1]
	v_cvt_pk_bf16_f32 v34, v34, v35
	v_cvt_pk_bf16_f32 v35, v36, v37
	v_mfma_f32_16x16x32_bf16 v[28:31], v[40:43], v[28:31], 0
	v_mfma_f32_16x16x32_bf16 v[36:39], v[40:43], v[24:27], 0
	v_mfma_f32_16x16x32_bf16 v[24:27], v[32:35], v[24:27], v[28:31]
	s_nop 5
	ds_read_b128 v[28:31], v113 offset:128
	ds_read_b128 v[32:35], v113 offset:144
	s_waitcnt lgkmcnt(1)
	v_cvt_pk_bf16_f32 v40, v28, v29
	v_cvt_pk_bf16_f32 v41, v30, v31
	v_lshlrev_b32_e32 v44, 16, v40
	v_and_b32_e32 v45, 0xffff0000, v40
	v_pk_add_f32 v[28:29], v[28:29], v[44:45] neg_lo:[0,1] neg_hi:[0,1]
	v_lshlrev_b32_e32 v44, 16, v41
	v_and_b32_e32 v45, 0xffff0000, v41
	s_waitcnt lgkmcnt(0)
; __device__ __forceinline__ unsigned cvt_pk(float lo, float hi) { f32x2_t v = {lo, hi}; bf16x2_t b = __builtin_convertvector(v, bf16x2_t); return __builtin_bit_cast(unsigned, b); }
; __device__ __forceinline__ float bf2f(unsigned short h) { return __uint_as_float(((unsigned)h) << 16); }
; __device__ __forceinline__ float bflo(unsigned w) { return __uint_as_float(w << 16); }
; __device__ __forceinline__ float bfhi(unsigned w) { return __uint_as_float(w & 0xffff0000u); }
; __device__ __forceinline__ unsigned short f2bf(float f) { return (unsigned short)(cvt_pk(f, 0.f) & 0xffffu); }
; __device__ __forceinline__ void s5_unit(ArgsP A, int l, int unit, unsigned char* lds, int wave_, int lane_) {
;     ...
;             for (int ks = 0; ks < 4; ++ks) { const float* hp = Hs + (lane & 15) * 132 + 32 * ks + 8 * (lane >> 4); const f32x4 h0 = *(const f32x4*)hp, h1 = *(const f32x4*)(hp + 4);
;                 u32x4 wh; wh.x = cvt_pk(h0[0], h0[1]); wh.y = cvt_pk(h0[2], h0[3]); wh.z = cvt_pk(h1[0], h1[1]); wh.w = cvt_pk(h1[2], h1[3]);
;                 u32x4 wl; wl.x = cvt_pk(h0[0] - bflo(wh.x), h0[1] - bfhi(wh.x)); wl.y = cvt_pk(h0[2] - bflo(wh.y), h0[3] - bfhi(wh.y)); wl.z = cvt_pk(h1[0] - bflo(wh.z), h1[1] - bfhi(wh.z)); wl.w = cvt_pk(h1[2] - bflo(wh.w), h1[3] - bfhi(wh.w));
;                 const bf16x8 hh_ = __builtin_bit_cast(bf16x8, wh), hl_ = __builtin_bit_cast(bf16x8, wl);
;                 y = __builtin_amdgcn_mfma_f32_16x16x32_bf16(hh_, chl[2 * ks], y, 0, 0, 0); y2 = __builtin_amdgcn_mfma_f32_16x16x32_bf16(hh_, chl[2 * ks + 1], y2, 0, 0, 0);
;                 y2 = __builtin_amdgcn_mfma_f32_16x16x32_bf16(hl_, chl[2 * ks], y2, 0, 0, 0); }
;             y = y + y2;
; #pragma unroll
;             for (int i = 0; i < 4; ++i) { const int t = 16 * blk + 4 * (lane >> 4) + i; const int col = 16 * g + (lane & 15);
;                 const float uval = bf2f(uraw[i]); const float v = gelu_tanh(y[i] + dv * uval); ys[t * YS_STRIDE + col] = f2bf(v); }
;             __builtin_amdgcn_wave_barrier(); asm volatile("s_waitcnt lgkmcnt(0)" ::: "memory");
;         }
	v_cvt_pk_bf16_f32 v42, v32, v33
	v_cvt_pk_bf16_f32 v43, v34, v35
	v_pk_add_f32 v[30:31], v[30:31], v[44:45] neg_lo:[0,1] neg_hi:[0,1]
	v_cvt_pk_bf16_f32 v28, v28, v29
	v_cvt_pk_bf16_f32 v29, v30, v31
	v_lshlrev_b32_e32 v30, 16, v42
	v_and_b32_e32 v31, 0xffff0000, v42
	v_pk_add_f32 v[30:31], v[32:33], v[30:31] neg_lo:[0,1] neg_hi:[0,1]
	v_lshlrev_b32_e32 v32, 16, v43
	v_and_b32_e32 v33, 0xffff0000, v43
	v_pk_add_f32 v[32:33], v[34:35], v[32:33] neg_lo:[0,1] neg_hi:[0,1]
	v_cvt_pk_bf16_f32 v30, v30, v31
	v_cvt_pk_bf16_f32 v31, v32, v33
	v_mfma_f32_16x16x32_bf16 v[20:23], v[40:43], v[20:23], v[24:27]
	v_mfma_f32_16x16x32_bf16 v[32:35], v[40:43], v[16:19], v[36:39]
	v_mfma_f32_16x16x32_bf16 v[16:19], v[28:31], v[16:19], v[20:23]
	s_nop 5
	ds_read_b128 v[20:23], v113 offset:256
	ds_read_b128 v[24:27], v113 offset:272
	s_waitcnt lgkmcnt(1)
	v_cvt_pk_bf16_f32 v28, v20, v21
	v_cvt_pk_bf16_f32 v29, v22, v23
	v_lshlrev_b32_e32 v36, 16, v28
	v_and_b32_e32 v37, 0xffff0000, v28
	v_pk_add_f32 v[20:21], v[20:21], v[36:37] neg_lo:[0,1] neg_hi:[0,1]
	v_lshlrev_b32_e32 v36, 16, v29
	v_and_b32_e32 v37, 0xffff0000, v29
	s_waitcnt lgkmcnt(0)
	v_cvt_pk_bf16_f32 v30, v24, v25
	v_cvt_pk_bf16_f32 v31, v26, v27
	v_pk_add_f32 v[22:23], v[22:23], v[36:37] neg_lo:[0,1] neg_hi:[0,1]
	v_cvt_pk_bf16_f32 v20, v20, v21
	v_cvt_pk_bf16_f32 v21, v22, v23
	v_lshlrev_b32_e32 v22, 16, v30
	v_and_b32_e32 v23, 0xffff0000, v30
	v_pk_add_f32 v[22:23], v[24:25], v[22:23] neg_lo:[0,1] neg_hi:[0,1]
	v_lshlrev_b32_e32 v24, 16, v31
	v_and_b32_e32 v25, 0xffff0000, v31
	v_pk_add_f32 v[24:25], v[26:27], v[24:25] neg_lo:[0,1] neg_hi:[0,1]
	v_cvt_pk_bf16_f32 v22, v22, v23
	v_cvt_pk_bf16_f32 v23, v24, v25
	v_mfma_f32_16x16x32_bf16 v[12:15], v[28:31], v[12:15], v[16:19]
	v_mfma_f32_16x16x32_bf16 v[24:27], v[28:31], v[8:11], v[32:35]
	v_mfma_f32_16x16x32_bf16 v[8:11], v[20:23], v[8:11], v[12:15]
	s_nop 5
	ds_read_b128 v[12:15], v113 offset:384
	ds_read_b128 v[16:19], v113 offset:400
	s_waitcnt lgkmcnt(1)
	v_cvt_pk_bf16_f32 v20, v12, v13
	v_cvt_pk_bf16_f32 v21, v14, v15
	v_lshlrev_b32_e32 v28, 16, v20
	v_and_b32_e32 v29, 0xffff0000, v20
	v_pk_add_f32 v[12:13], v[12:13], v[28:29] neg_lo:[0,1] neg_hi:[0,1]
	v_lshlrev_b32_e32 v28, 16, v21
	v_and_b32_e32 v29, 0xffff0000, v21
	s_waitcnt lgkmcnt(0)
	v_cvt_pk_bf16_f32 v22, v16, v17
	v_cvt_pk_bf16_f32 v23, v18, v19
	v_pk_add_f32 v[14:15], v[14:15], v[28:29] neg_lo:[0,1] neg_hi:[0,1]
	v_cvt_pk_bf16_f32 v12, v12, v13
	v_cvt_pk_bf16_f32 v13, v14, v15
	v_lshlrev_b32_e32 v14, 16, v22
	v_and_b32_e32 v15, 0xffff0000, v22
	v_pk_add_f32 v[14:15], v[16:17], v[14:15] neg_lo:[0,1] neg_hi:[0,1]
	v_lshlrev_b32_e32 v16, 16, v23
	v_and_b32_e32 v17, 0xffff0000, v23
	v_pk_add_f32 v[16:17], v[18:19], v[16:17] neg_lo:[0,1] neg_hi:[0,1]
	v_cvt_pk_bf16_f32 v14, v14, v15
	v_cvt_pk_bf16_f32 v15, v16, v17
	v_mfma_f32_16x16x32_bf16 v[4:7], v[20:23], v[4:7], v[8:11]
	v_mfma_f32_16x16x32_bf16 v[16:19], v[20:23], v[0:3], v[24:27]
	v_mfma_f32_16x16x32_bf16 v[0:3], v[12:15], v[0:3], v[4:7]
	s_waitcnt vmcnt(3)
	s_nop 4
	v_lshlrev_b32_e32 v4, 16, v66
	s_nop 0
	v_pk_add_f32 v[0:1], v[16:17], v[0:1]
	v_pk_add_f32 v[2:3], v[18:19], v[2:3]
	v_fma_f32 v0, v79, v4, v0
	v_mul_f32_e32 v4, 0x3d372713, v0
	v_mul_f32_e32 v4, v0, v4
	v_fma_f32 v4, v0, v4, v0
	v_mul_f32_e32 v4, 0x3f4c422a, v4
	v_add_f32_e32 v4, v4, v4
	v_mul_f32_e32 v4, 0x3fb8aa3b, v4
	v_exp_f32_e32 v4, v4
	v_mul_f32_e32 v0, 0.5, v0
	v_add_f32_e32 v4, 1.0, v4
	v_rcp_f32_e32 v4, v4
	s_nop 0
	v_fma_f32 v4, v4, -2.0, 1.0
	v_add_f32_e32 v4, 1.0, v4
	v_mul_f32_e32 v0, v0, v4
	v_cvt_pk_bf16_f32 v0, v0, s0
	ds_write_b16 v102, v0 offset:49920
	s_waitcnt vmcnt(2)
	v_lshlrev_b32_e32 v0, 16, v67
	v_fmac_f32_e32 v1, v79, v0
	v_mul_f32_e32 v0, 0x3d372713, v1
	v_mul_f32_e32 v0, v1, v0
	v_fma_f32 v0, v1, v0, v1
	v_mul_f32_e32 v0, 0x3f4c422a, v0
	v_add_f32_e32 v0, v0, v0
	v_mul_f32_e32 v0, 0x3fb8aa3b, v0
	v_exp_f32_e32 v0, v0
	v_mul_f32_e32 v1, 0.5, v1
	v_add_f32_e32 v0, 1.0, v0
	v_rcp_f32_e32 v0, v0
	s_nop 0
	v_fma_f32 v0, v0, -2.0, 1.0
	v_add_f32_e32 v0, 1.0, v0
	v_mul_f32_e32 v0, v1, v0
	v_cvt_pk_bf16_f32 v0, v0, s0
	ds_write_b16 v102, v0 offset:50960
	s_waitcnt vmcnt(1)
	v_lshlrev_b32_e32 v0, 16, v68
	v_fma_f32 v0, v79, v0, v2
	v_mul_f32_e32 v1, 0x3d372713, v0
	v_mul_f32_e32 v1, v0, v1
	v_fma_f32 v1, v0, v1, v0
	v_mul_f32_e32 v1, 0x3f4c422a, v1
	v_add_f32_e32 v1, v1, v1
	v_mul_f32_e32 v1, 0x3fb8aa3b, v1
	v_exp_f32_e32 v1, v1
	v_mul_f32_e32 v0, 0.5, v0
	v_add_f32_e32 v1, 1.0, v1
	v_rcp_f32_e32 v1, v1
	s_nop 0
	v_fma_f32 v1, v1, -2.0, 1.0
	v_add_f32_e32 v1, 1.0, v1
	v_mul_f32_e32 v0, v0, v1
	v_cvt_pk_bf16_f32 v0, v0, s0
	ds_write_b16 v102, v0 offset:52000
	s_waitcnt vmcnt(0)
	v_lshlrev_b32_e32 v0, 16, v69
	v_fmac_f32_e32 v3, v79, v0
	v_mul_f32_e32 v0, 0x3d372713, v3
	v_mul_f32_e32 v0, v3, v0
	v_fma_f32 v0, v3, v0, v3
	v_mul_f32_e32 v0, 0x3f4c422a, v0
	v_add_f32_e32 v0, v0, v0
	v_mul_f32_e32 v0, 0x3fb8aa3b, v0
	v_exp_f32_e32 v0, v0
	v_mul_f32_e32 v1, 0.5, v3
	v_add_f32_e32 v0, 1.0, v0
	v_rcp_f32_e32 v0, v0
	s_nop 0
	v_fma_f32 v0, v0, -2.0, 1.0
	v_add_f32_e32 v0, 1.0, v0
	v_mul_f32_e32 v0, v1, v0
	v_cvt_pk_bf16_f32 v0, v0, s0
	ds_write_b16 v102, v0 offset:53040
	s_waitcnt lgkmcnt(0)
	s_cbranch_scc1 .LBB0_792
; __device__ __forceinline__ void s5_unit(ArgsP A, int l, int unit, unsigned char* lds, int wave_, int lane_) {
;     ...
;     const bf16_t* WG = (const bf16_t*)(A->ws + WS_W + (size_t)l * WL_SIZE + WL_WGLU);
;     f32x4 acc[4][4];
; #pragma unroll
;     for (int mb = 0; mb < 4; ++mb)
; #pragma unroll
;         for (int nb = 0; nb < 4; ++nb) acc[mb][nb] = (f32x4){0.f, 0.f, 0.f, 0.f};
;     {
;         const bf16_t* wb = WG + (size_t)(64 * wave + (lane & 15)) * 512 + 8 * (lane >> 4);
;         bf16x8 bq[4][4];
; #pragma unroll
;         for (int p = 0; p < 4; ++p)
; #pragma unroll
;             for (int nb = 0; nb < 4; ++nb) bq[p][nb] = *(const bf16x8*)(wb + (size_t)(16 * nb) * 512 + 32 * p);
; #pragma unroll
;         for (int ks = 0; ks < 16; ++ks) {
;             bf16x8 af[4];
; #pragma unroll
;             for (int mb = 0; mb < 4; ++mb) af[mb] = *(const bf16x8*)(ys + (16 * mb + (lane & 15)) * YS_STRIDE + 32 * ks + 8 * (lane >> 4));
;             asm volatile("" : "+v"(bq[ks & 3][0]), "+v"(bq[ks & 3][1]), "+v"(bq[ks & 3][2]), "+v"(bq[ks & 3][3]) :: "memory");
; #pragma unroll
;             for (int mb = 0; mb < 4; ++mb)
; #pragma unroll
;                 for (int nb = 0; nb < 4; ++nb) acc[mb][nb] = __builtin_amdgcn_mfma_f32_16x16x32_bf16(af[mb], bq[ks & 3][nb], acc[mb][nb], 0, 0, 0);
;             if (ks + 4 < 16) {
; #pragma unroll
;                 for (int nb = 0; nb < 4; ++nb) bq[ks & 3][nb] = *(const bf16x8*)(wb + (size_t)(16 * nb) * 512 + 32 * (ks + 4));
;             }
;         }
;     }
	s_mul_i32 s5, s92, 0xa7c0000
	s_load_dwordx2 s[100:101], s[26:27], 0xb0
	s_and_b32 s4, s11, 0x1ff
	v_lshrrev_b32_e32 v150, 4, v105
	v_mul_u32_u24_e32 v151, 0x410, v104
	s_add_u32 s6, s2, s5
	s_addc_u32 s7, s3, 0
	s_add_u32 s6, s6, 0xa650000
	s_addc_u32 s7, s7, 0
	v_or_b32_e32 v144, s4, v104
	v_lshlrev_b32_e32 v144, 10, v144
	v_lshl_add_u32 v144, v150, 4, v144
	v_lshl_add_u32 v148, v150, 4, v151
	v_add_u32_e32 v148, 16, v148
	s_lshl_b32 s5, s4, 1
	v_lshl_add_u32 v149, v150, 3, v151
	v_add_u32_e32 v149, s5, v149
	v_add_u32_e32 v149, 16, v149
	s_lshr_b32 s5, s4, 6
	s_mul_i32 s5, s5, 0x2400
	s_add_i32 s5, s5, 0x10410
	v_mul_u32_u24_e32 v152, 0x90, v104
	v_lshl_add_u32 v152, v150, 3, v152
	v_add_u32_e32 v152, s5, v152
	v_lshrrev_b32_e32 v153, 3, v105
	v_and_b32_e32 v154, 7, v105
	v_mul_u32_u24_e32 v155, 0x90, v153
	v_lshl_add_u32 v155, v154, 4, v155
	v_add_u32_e32 v155, s5, v155
	v_lshlrev_b32_e32 v156, 2, v150
	v_add_lshl_u32 v156, v156, s11, 2
	v_add_u32_e32 v157, s10, v153
	v_lshlrev_b32_e32 v157, 12, v157
	v_lshl_add_u32 v157, v154, 4, v157
	s_lshl_b32 s5, s4, 1
	v_add_u32_e32 v157, s5, v157
	s_waitcnt lgkmcnt(0)
	s_barrier
	global_load_dwordx4 v[16:19], v144, s[6:7]
	global_load_dwordx4 v[20:23], v144, s[6:7] offset:64
	global_load_dwordx4 v[24:27], v144, s[6:7] offset:128
	global_load_dwordx4 v[28:31], v144, s[6:7] offset:192
	global_load_dwordx4 v[32:35], v144, s[6:7] offset:256
	global_load_dwordx4 v[36:39], v144, s[6:7] offset:320
	global_load_dwordx4 v[40:43], v144, s[6:7] offset:384
	global_load_dwordx4 v[44:47], v144, s[6:7] offset:448
	ds_read_b128 v[48:51], v148
	ds_read_b128 v[52:55], v148 offset:16640
	ds_read_b128 v[56:59], v148 offset:33280
	ds_read_b128 v[60:63], v148 offset:49920
	ds_read_b128 v[64:67], v148 offset:64
	ds_read_b128 v[68:71], v148 offset:16704
	ds_read_b128 v[72:75], v148 offset:33344
	ds_read_b128 v[76:79], v148 offset:49984
	ds_read_b128 v[80:83], v148 offset:128
	ds_read_b128 v[84:87], v148 offset:16768
	ds_read_b128 v[88:91], v148 offset:33408
	ds_read_b128 v[92:95], v148 offset:50048
	s_mov_b32 s4, 0
.Ls5g_nb:
	global_load_dwordx4 v[120:123], v156, s[100:101]
	v_mov_b32_e32 v0, 0
	v_mov_b32_e32 v1, 0
	v_mov_b32_e32 v2, 0
	v_mov_b32_e32 v3, 0
	v_mov_b32_e32 v4, 0
	v_mov_b32_e32 v5, 0
	v_mov_b32_e32 v6, 0
	v_mov_b32_e32 v7, 0
	v_mov_b32_e32 v8, 0
	v_mov_b32_e32 v9, 0
	v_mov_b32_e32 v10, 0
	v_mov_b32_e32 v11, 0
	v_mov_b32_e32 v12, 0
	v_mov_b32_e32 v13, 0
	v_mov_b32_e32 v14, 0
	v_mov_b32_e32 v15, 0
	v_mov_b32_e32 v145, v144
	v_mov_b32_e32 v146, v148
	v_add_u32_e32 v147, 0x200, v148
	s_mov_b32 s5, 0
.Ls5g_k:
	s_cmp_lg_u32 s5, 1
	s_cbranch_scc1 .Ls5g_k1
	v_add_u32_e32 v145, 0x3e00, v144
	v_mov_b32_e32 v147, v148
.Ls5g_k1:
	ds_read_b128 v[96:99], v146 offset:192
	ds_read_b128 v[100:103], v146 offset:16832
	ds_read_b128 v[104:107], v146 offset:33472
	ds_read_b128 v[108:111], v146 offset:50112
	s_waitcnt vmcnt(7) lgkmcnt(12)
	v_mfma_f32_16x16x32_bf16 v[0:3], v[16:19], v[48:51], v[0:3]
	v_mfma_f32_16x16x32_bf16 v[4:7], v[16:19], v[52:55], v[4:7]
	v_mfma_f32_16x16x32_bf16 v[8:11], v[16:19], v[56:59], v[8:11]
	v_mfma_f32_16x16x32_bf16 v[12:15], v[16:19], v[60:63], v[12:15]
	global_load_dwordx4 v[16:19], v145, s[6:7] offset:512
	ds_read_b128 v[48:51], v146 offset:256
	ds_read_b128 v[52:55], v146 offset:16896
	ds_read_b128 v[56:59], v146 offset:33536
	ds_read_b128 v[60:63], v146 offset:50176
	s_waitcnt vmcnt(7) lgkmcnt(12)
	v_mfma_f32_16x16x32_bf16 v[0:3], v[20:23], v[64:67], v[0:3]
	v_mfma_f32_16x16x32_bf16 v[4:7], v[20:23], v[68:71], v[4:7]
	v_mfma_f32_16x16x32_bf16 v[8:11], v[20:23], v[72:75], v[8:11]
	v_mfma_f32_16x16x32_bf16 v[12:15], v[20:23], v[76:79], v[12:15]
	global_load_dwordx4 v[20:23], v145, s[6:7] offset:576
	ds_read_b128 v[64:67], v146 offset:320
	ds_read_b128 v[68:71], v146 offset:16960
	ds_read_b128 v[72:75], v146 offset:33600
	ds_read_b128 v[76:79], v146 offset:50240
	s_waitcnt vmcnt(7) lgkmcnt(12)
	v_mfma_f32_16x16x32_bf16 v[0:3], v[24:27], v[80:83], v[0:3]
	v_mfma_f32_16x16x32_bf16 v[4:7], v[24:27], v[84:87], v[4:7]
	v_mfma_f32_16x16x32_bf16 v[8:11], v[24:27], v[88:91], v[8:11]
	v_mfma_f32_16x16x32_bf16 v[12:15], v[24:27], v[92:95], v[12:15]
	global_load_dwordx4 v[24:27], v145, s[6:7] offset:640
	ds_read_b128 v[80:83], v146 offset:384
	ds_read_b128 v[84:87], v146 offset:17024
	ds_read_b128 v[88:91], v146 offset:33664
	ds_read_b128 v[92:95], v146 offset:50304
	s_waitcnt vmcnt(7) lgkmcnt(12)
	v_mfma_f32_16x16x32_bf16 v[0:3], v[28:31], v[96:99], v[0:3]
	v_mfma_f32_16x16x32_bf16 v[4:7], v[28:31], v[100:103], v[4:7]
	v_mfma_f32_16x16x32_bf16 v[8:11], v[28:31], v[104:107], v[8:11]
	v_mfma_f32_16x16x32_bf16 v[12:15], v[28:31], v[108:111], v[12:15]
	global_load_dwordx4 v[28:31], v145, s[6:7] offset:704
	ds_read_b128 v[96:99], v146 offset:448
	ds_read_b128 v[100:103], v146 offset:17088
	ds_read_b128 v[104:107], v146 offset:33728
	ds_read_b128 v[108:111], v146 offset:50368
	s_waitcnt vmcnt(7) lgkmcnt(12)
	v_mfma_f32_16x16x32_bf16 v[0:3], v[32:35], v[48:51], v[0:3]
	v_mfma_f32_16x16x32_bf16 v[4:7], v[32:35], v[52:55], v[4:7]
	v_mfma_f32_16x16x32_bf16 v[8:11], v[32:35], v[56:59], v[8:11]
	v_mfma_f32_16x16x32_bf16 v[12:15], v[32:35], v[60:63], v[12:15]
	global_load_dwordx4 v[32:35], v145, s[6:7] offset:768
	ds_read_b128 v[48:51], v147
	ds_read_b128 v[52:55], v147 offset:16640
	ds_read_b128 v[56:59], v147 offset:33280
	ds_read_b128 v[60:63], v147 offset:49920
	s_waitcnt vmcnt(7) lgkmcnt(12)
	v_mfma_f32_16x16x32_bf16 v[0:3], v[36:39], v[64:67], v[0:3]
	v_mfma_f32_16x16x32_bf16 v[4:7], v[36:39], v[68:71], v[4:7]
	v_mfma_f32_16x16x32_bf16 v[8:11], v[36:39], v[72:75], v[8:11]
	v_mfma_f32_16x16x32_bf16 v[12:15], v[36:39], v[76:79], v[12:15]
	global_load_dwordx4 v[36:39], v145, s[6:7] offset:832
	ds_read_b128 v[64:67], v147 offset:64
	ds_read_b128 v[68:71], v147 offset:16704
	ds_read_b128 v[72:75], v147 offset:33344
	ds_read_b128 v[76:79], v147 offset:49984
	s_waitcnt vmcnt(7) lgkmcnt(12)
	v_mfma_f32_16x16x32_bf16 v[0:3], v[40:43], v[80:83], v[0:3]
	v_mfma_f32_16x16x32_bf16 v[4:7], v[40:43], v[84:87], v[4:7]
	v_mfma_f32_16x16x32_bf16 v[8:11], v[40:43], v[88:91], v[8:11]
	v_mfma_f32_16x16x32_bf16 v[12:15], v[40:43], v[92:95], v[12:15]
	global_load_dwordx4 v[40:43], v145, s[6:7] offset:896
	ds_read_b128 v[80:83], v147 offset:128
	ds_read_b128 v[84:87], v147 offset:16768
	ds_read_b128 v[88:91], v147 offset:33408
	ds_read_b128 v[92:95], v147 offset:50048
	s_waitcnt vmcnt(7) lgkmcnt(12)
	v_mfma_f32_16x16x32_bf16 v[0:3], v[44:47], v[96:99], v[0:3]
	v_mfma_f32_16x16x32_bf16 v[4:7], v[44:47], v[100:103], v[4:7]
	v_mfma_f32_16x16x32_bf16 v[8:11], v[44:47], v[104:107], v[8:11]
	v_mfma_f32_16x16x32_bf16 v[12:15], v[44:47], v[108:111], v[12:15]
	global_load_dwordx4 v[44:47], v145, s[6:7] offset:960
	v_add_u32_e32 v145, 0x200, v145
	v_add_u32_e32 v146, 0x200, v146
	v_add_u32_e32 v147, 0x200, v147
	s_add_i32 s5, s5, 1
	s_cmp_lt_u32 s5, 2
	s_cbranch_scc1 .Ls5g_k
; __device__ __forceinline__ float bf2f(unsigned short h) { return __uint_as_float(((unsigned)h) << 16); }
; __device__ __forceinline__ unsigned short f2bf(float f) { return (unsigned short)(cvt_pk(f, 0.f) & 0xffffu); }
; __device__ __forceinline__ float sigmoidf_(float x) { return fast_rcp(1.f + fast_exp2(-x * LOG2E)); }
; __device__ __forceinline__ void s5_unit(ArgsP A, int l, int unit, unsigned char* lds, int wave_, int lane_) {
;     ...
;     bf16_t* MIX = (bf16_t*)(A->ws + WS_MIX);
;     float bglv[4];
; #pragma unroll
;     for (int nb = 0; nb < 4; ++nb) bglv[nb] = A->in[22][l * 512 + 64 * wave + 16 * nb + (lane & 15)];
; #pragma unroll
;     for (int nb = 0; nb < 4; ++nb) { const int n = 64 * wave + 16 * nb + (lane & 15); const float bgl = bglv[nb];
; #pragma unroll
;         for (int mb = 0; mb < 4; ++mb)
; #pragma unroll
;             for (int i = 0; i < 4; ++i) { const int t = 16 * mb + 4 * (lane >> 4) + i; const float yv = bf2f(ys[t * YS_STRIDE + n]);
;                 MIX[(size_t)(rowbase + t) * DM + n] = f2bf(yv * sigmoidf_(acc[mb][nb][i] + bgl)); } }
;     __syncthreads();
	ds_read_b64 v[112:113], v149
	ds_read_b64 v[114:115], v149 offset:16640
	ds_read_b64 v[116:117], v149 offset:33280
	ds_read_b64 v[118:119], v149 offset:49920
	s_nop 7
	s_waitcnt vmcnt(8) lgkmcnt(0)
	v_add_f32_e32 v124, v0, v120
	v_add_f32_e32 v125, v1, v121
	v_add_f32_e32 v126, v2, v122
	v_add_f32_e32 v127, v3, v123
	v_mul_f32_e32 v124, 0xbfb8aa3b, v124
	v_mul_f32_e32 v125, 0xbfb8aa3b, v125
	v_mul_f32_e32 v126, 0xbfb8aa3b, v126
	v_mul_f32_e32 v127, 0xbfb8aa3b, v127
	v_exp_f32_e32 v124, v124
	v_exp_f32_e32 v125, v125
	v_exp_f32_e32 v126, v126
	v_exp_f32_e32 v127, v127
	v_lshlrev_b32_e32 v128, 16, v112
	v_and_b32_e32 v129, 0xffff0000, v112
	v_add_f32_e32 v124, 1.0, v124
	v_add_f32_e32 v125, 1.0, v125
	v_add_f32_e32 v126, 1.0, v126
	v_add_f32_e32 v127, 1.0, v127
	v_lshlrev_b32_e32 v130, 16, v113
	v_and_b32_e32 v131, 0xffff0000, v113
	v_rcp_f32_e32 v124, v124
	v_rcp_f32_e32 v125, v125
	v_rcp_f32_e32 v126, v126
	v_rcp_f32_e32 v127, v127
	s_nop 0
	v_mul_f32_e32 v128, v128, v124
	v_mul_f32_e32 v129, v129, v125
	v_mul_f32_e32 v130, v130, v126
	v_mul_f32_e32 v131, v131, v127
	v_cvt_pk_bf16_f32 v132, v128, v129
	v_cvt_pk_bf16_f32 v133, v130, v131
	ds_write_b64 v152, v[132:133]
	v_add_f32_e32 v124, v4, v120
	v_add_f32_e32 v125, v5, v121
	v_add_f32_e32 v126, v6, v122
	v_add_f32_e32 v127, v7, v123
	v_mul_f32_e32 v124, 0xbfb8aa3b, v124
	v_mul_f32_e32 v125, 0xbfb8aa3b, v125
	v_mul_f32_e32 v126, 0xbfb8aa3b, v126
	v_mul_f32_e32 v127, 0xbfb8aa3b, v127
	v_exp_f32_e32 v124, v124
	v_exp_f32_e32 v125, v125
	v_exp_f32_e32 v126, v126
	v_exp_f32_e32 v127, v127
	v_lshlrev_b32_e32 v128, 16, v114
	v_and_b32_e32 v129, 0xffff0000, v114
	v_add_f32_e32 v124, 1.0, v124
	v_add_f32_e32 v125, 1.0, v125
	v_add_f32_e32 v126, 1.0, v126
	v_add_f32_e32 v127, 1.0, v127
	v_lshlrev_b32_e32 v130, 16, v115
	v_and_b32_e32 v131, 0xffff0000, v115
	v_rcp_f32_e32 v124, v124
	v_rcp_f32_e32 v125, v125
	v_rcp_f32_e32 v126, v126
	v_rcp_f32_e32 v127, v127
	s_nop 0
	v_mul_f32_e32 v128, v128, v124
	v_mul_f32_e32 v129, v129, v125
	v_mul_f32_e32 v130, v130, v126
	v_mul_f32_e32 v131, v131, v127
	v_cvt_pk_bf16_f32 v132, v128, v129
	v_cvt_pk_bf16_f32 v133, v130, v131
	ds_write_b64 v152, v[132:133] offset:2304
	v_add_f32_e32 v124, v8, v120
	v_add_f32_e32 v125, v9, v121
	v_add_f32_e32 v126, v10, v122
	v_add_f32_e32 v127, v11, v123
	v_mul_f32_e32 v124, 0xbfb8aa3b, v124
	v_mul_f32_e32 v125, 0xbfb8aa3b, v125
	v_mul_f32_e32 v126, 0xbfb8aa3b, v126
	v_mul_f32_e32 v127, 0xbfb8aa3b, v127
	v_exp_f32_e32 v124, v124
	v_exp_f32_e32 v125, v125
	v_exp_f32_e32 v126, v126
	v_exp_f32_e32 v127, v127
	v_lshlrev_b32_e32 v128, 16, v116
	v_and_b32_e32 v129, 0xffff0000, v116
	v_add_f32_e32 v124, 1.0, v124
	v_add_f32_e32 v125, 1.0, v125
	v_add_f32_e32 v126, 1.0, v126
	v_add_f32_e32 v127, 1.0, v127
	v_lshlrev_b32_e32 v130, 16, v117
	v_and_b32_e32 v131, 0xffff0000, v117
	v_rcp_f32_e32 v124, v124
	v_rcp_f32_e32 v125, v125
	v_rcp_f32_e32 v126, v126
	v_rcp_f32_e32 v127, v127
	s_nop 0
	v_mul_f32_e32 v128, v128, v124
	v_mul_f32_e32 v129, v129, v125
	v_mul_f32_e32 v130, v130, v126
	v_mul_f32_e32 v131, v131, v127
	v_cvt_pk_bf16_f32 v132, v128, v129
	v_cvt_pk_bf16_f32 v133, v130, v131
	ds_write_b64 v152, v[132:133] offset:4608
	v_add_f32_e32 v124, v12, v120
	v_add_f32_e32 v125, v13, v121
	v_add_f32_e32 v126, v14, v122
	v_add_f32_e32 v127, v15, v123
	v_mul_f32_e32 v124, 0xbfb8aa3b, v124
	v_mul_f32_e32 v125, 0xbfb8aa3b, v125
	v_mul_f32_e32 v126, 0xbfb8aa3b, v126
	v_mul_f32_e32 v127, 0xbfb8aa3b, v127
	v_exp_f32_e32 v124, v124
	v_exp_f32_e32 v125, v125
	v_exp_f32_e32 v126, v126
	v_exp_f32_e32 v127, v127
	v_lshlrev_b32_e32 v128, 16, v118
	v_and_b32_e32 v129, 0xffff0000, v118
	v_add_f32_e32 v124, 1.0, v124
	v_add_f32_e32 v125, 1.0, v125
	v_add_f32_e32 v126, 1.0, v126
	v_add_f32_e32 v127, 1.0, v127
	v_lshlrev_b32_e32 v130, 16, v119
	v_and_b32_e32 v131, 0xffff0000, v119
	v_rcp_f32_e32 v124, v124
	v_rcp_f32_e32 v125, v125
	v_rcp_f32_e32 v126, v126
	v_rcp_f32_e32 v127, v127
	s_nop 0
	v_mul_f32_e32 v128, v128, v124
	v_mul_f32_e32 v129, v129, v125
	v_mul_f32_e32 v130, v130, v126
	v_mul_f32_e32 v131, v131, v127
	v_cvt_pk_bf16_f32 v132, v128, v129
	v_cvt_pk_bf16_f32 v133, v130, v131
	ds_write_b64 v152, v[132:133] offset:6912
	v_add_u32_e32 v144, 0x4000, v144
	v_add_u32_e32 v149, 32, v149
	v_add_u32_e32 v152, 32, v152
	v_add_u32_e32 v156, 64, v156
	s_add_i32 s4, s4, 1
	s_cmp_lt_u32 s4, 4
	s_cbranch_scc1 .Ls5g_nb
	s_waitcnt lgkmcnt(0)
	s_add_u32 s4, s2, 0x24f90000
	s_addc_u32 s5, s3, 0
	ds_read_b128 v[64:67], v155
	ds_read_b128 v[68:71], v155 offset:1152
	ds_read_b128 v[72:75], v155 offset:2304
	ds_read_b128 v[76:79], v155 offset:3456
	ds_read_b128 v[80:83], v155 offset:4608
	ds_read_b128 v[84:87], v155 offset:5760
	ds_read_b128 v[88:91], v155 offset:6912
	ds_read_b128 v[92:95], v155 offset:8064
	v_add_u32_e32 v158, 0x8000, v157
	v_add_u32_e32 v159, 0x8000, v158
	v_add_u32_e32 v160, 0x8000, v159
	v_add_u32_e32 v161, 0x8000, v160
	v_add_u32_e32 v162, 0x8000, v161
	v_add_u32_e32 v163, 0x8000, v162
	v_add_u32_e32 v164, 0x8000, v163
	s_waitcnt lgkmcnt(7)
	global_store_dwordx4 v157, v[64:67], s[4:5]
	s_waitcnt lgkmcnt(6)
	global_store_dwordx4 v158, v[68:71], s[4:5]
	s_waitcnt lgkmcnt(5)
	global_store_dwordx4 v159, v[72:75], s[4:5]
	s_waitcnt lgkmcnt(4)
	global_store_dwordx4 v160, v[76:79], s[4:5]
	s_waitcnt lgkmcnt(3)
	global_store_dwordx4 v161, v[80:83], s[4:5]
	s_waitcnt lgkmcnt(2)
	global_store_dwordx4 v162, v[84:87], s[4:5]
	s_waitcnt lgkmcnt(1)
	global_store_dwordx4 v163, v[88:91], s[4:5]
	s_waitcnt lgkmcnt(0)
	global_store_dwordx4 v164, v[92:95], s[4:5]
	s_waitcnt vmcnt(8)
	s_mov_b64 s[2:3], 0
	s_barrier
	s_branch .LBB0_785
